# MFMA order: same-accumulator k0,k1 MFMAs back-to-back (SrcC forwarding), on combo4
# speedup vs baseline: 1.0143x; 1.0143x over previous
.LBB0_175:
	s_add_i32 s29, s29, 2
	s_mov_b32 s44, s29
	s_ashr_i32 s45, s44, 31
	s_lshl_b64 s[82:83], s[44:45], 7
	s_add_u32 s45, s82, 0x100
	s_addc_u32 s81, s83, 0
	s_add_u32 s84, s42, s45
	s_addc_u32 s85, s43, s81
	s_add_u32 s86, s40, s45
	s_addc_u32 s81, s41, s81
	s_cmp_eq_u32 s44, 14
	s_cselect_b32 s45, s75, s85
	s_cselect_b32 s44, s76, s84
	s_cselect_b32 s85, s31, s81
	s_cselect_b32 s84, s74, s86
	s_add_u32 s82, s42, s82
	s_addc_u32 s83, s43, s83
	v_lshl_add_u64 v[212:213], s[82:83], 0, v[130:131]
	s_mov_b32 m0, s66
	v_lshl_add_u64 v[214:215], v[212:213], 0, s[22:23]
	global_load_lds_dwordx4 v[214:215], off
	v_lshl_add_u64 v[212:213], v[212:213], 0, s[24:25]
	s_mov_b32 m0, s67
	s_nop 0
	global_load_lds_dwordx4 v[212:213], off
	ds_read_b128 v[146:149], v141
	ds_read_b128 v[150:153], v141 offset:1024
	ds_read_b128 v[154:157], v141 offset:2048
	ds_read_b128 v[158:161], v141 offset:3072
	ds_read_b128 v[162:165], v142
	ds_read_b128 v[166:169], v142 offset:1024
	ds_read_b128 v[170:173], v142 offset:2048
	ds_read_b128 v[174:177], v142 offset:3072
	ds_read_b128 v[178:181], v143
	ds_read_b128 v[182:185], v143 offset:1024
	ds_read_b128 v[186:189], v143 offset:2048
	ds_read_b128 v[190:193], v143 offset:3072
	ds_read_b128 v[194:197], v143 offset:4096
	ds_read_b128 v[198:201], v143 offset:5120
	ds_read_b128 v[202:205], v143 offset:6144
	ds_read_b128 v[206:209], v143 offset:7168
	s_waitcnt vmcnt(8)
	s_waitcnt lgkmcnt(0)
	s_barrier
	s_waitcnt lgkmcnt(0)
	v_mfma_f32_16x16x32_bf16 v[124:127], v[146:149], v[178:181], v[124:127]
	v_mfma_f32_16x16x32_bf16 v[124:127], v[150:153], v[182:185], v[124:127]
	v_mfma_f32_16x16x32_bf16 v[112:115], v[154:157], v[178:181], v[112:115]
	v_mfma_f32_16x16x32_bf16 v[112:115], v[158:161], v[182:185], v[112:115]
	v_mfma_f32_16x16x32_bf16 v[120:123], v[162:165], v[178:181], v[120:123]
	v_mfma_f32_16x16x32_bf16 v[120:123], v[166:169], v[182:185], v[120:123]
	v_mfma_f32_16x16x32_bf16 v[116:119], v[170:173], v[178:181], v[116:119]
	v_mfma_f32_16x16x32_bf16 v[116:119], v[174:177], v[182:185], v[116:119]
	v_mfma_f32_16x16x32_bf16 v[100:103], v[170:173], v[186:189], v[100:103]
	v_mfma_f32_16x16x32_bf16 v[100:103], v[174:177], v[190:193], v[100:103]
	v_mfma_f32_16x16x32_bf16 v[104:107], v[162:165], v[186:189], v[104:107]
	v_mfma_f32_16x16x32_bf16 v[104:107], v[166:169], v[190:193], v[104:107]
	v_mfma_f32_16x16x32_bf16 v[96:99], v[154:157], v[186:189], v[96:99]
	v_mfma_f32_16x16x32_bf16 v[96:99], v[158:161], v[190:193], v[96:99]
	v_mfma_f32_16x16x32_bf16 v[108:111], v[146:149], v[186:189], v[108:111]
	v_mfma_f32_16x16x32_bf16 v[108:111], v[150:153], v[190:193], v[108:111]
	v_mfma_f32_16x16x32_bf16 v[92:95], v[146:149], v[194:197], v[92:95]
	v_mfma_f32_16x16x32_bf16 v[92:95], v[150:153], v[198:201], v[92:95]
	v_mfma_f32_16x16x32_bf16 v[80:83], v[154:157], v[194:197], v[80:83]
	v_mfma_f32_16x16x32_bf16 v[80:83], v[158:161], v[198:201], v[80:83]
	v_mfma_f32_16x16x32_bf16 v[88:91], v[162:165], v[194:197], v[88:91]
	v_mfma_f32_16x16x32_bf16 v[88:91], v[166:169], v[198:201], v[88:91]
	v_mfma_f32_16x16x32_bf16 v[84:87], v[170:173], v[194:197], v[84:87]
	v_mfma_f32_16x16x32_bf16 v[84:87], v[174:177], v[198:201], v[84:87]
	v_mfma_f32_16x16x32_bf16 v[68:71], v[170:173], v[202:205], v[68:71]
	v_mfma_f32_16x16x32_bf16 v[68:71], v[174:177], v[206:209], v[68:71]
	v_mfma_f32_16x16x32_bf16 v[72:75], v[162:165], v[202:205], v[72:75]
	v_mfma_f32_16x16x32_bf16 v[72:75], v[166:169], v[206:209], v[72:75]
	v_mfma_f32_16x16x32_bf16 v[64:67], v[154:157], v[202:205], v[64:67]
	v_mfma_f32_16x16x32_bf16 v[64:67], v[158:161], v[206:209], v[64:67]
	v_mfma_f32_16x16x32_bf16 v[76:79], v[146:149], v[202:205], v[76:79]
	v_mfma_f32_16x16x32_bf16 v[76:79], v[150:153], v[206:209], v[76:79]
	s_barrier
	s_mov_b32 m0, s68
	v_lshl_add_u64 v[212:213], s[84:85], 0, v[128:129]
	global_load_lds_dwordx4 v[212:213], off
	v_lshl_add_u64 v[214:215], v[212:213], 0, s[0:1]
	s_mov_b32 m0, s69
	s_nop 0
	global_load_lds_dwordx4 v[214:215], off
	v_lshl_add_u64 v[214:215], v[212:213], 0, s[2:3]
	s_mov_b32 m0, s70
	s_nop 0
	global_load_lds_dwordx4 v[214:215], off
	v_lshl_add_u64 v[214:215], v[212:213], 0, s[8:9]
	s_mov_b32 m0, s71
	s_nop 0
	global_load_lds_dwordx4 v[214:215], off
	v_lshl_add_u64 v[214:215], s[44:45], 0, v[130:131]
	s_mov_b32 m0, s39
	v_lshl_add_u64 v[216:217], v[214:215], 0, s[0:1]
	global_load_lds_dwordx4 v[214:215], off
	s_mov_b32 m0, s56
	s_nop 0
	global_load_lds_dwordx4 v[216:217], off
	ds_read_b128 v[178:181], v143 offset:16384
	ds_read_b128 v[182:185], v143 offset:17408
	ds_read_b128 v[186:189], v143 offset:18432
	ds_read_b128 v[190:193], v143 offset:19456
	ds_read_b128 v[194:197], v143 offset:20480
	ds_read_b128 v[198:201], v143 offset:21504
	ds_read_b128 v[202:205], v143 offset:22528
	ds_read_b128 v[206:209], v143 offset:23552
	s_waitcnt vmcnt(8)
	s_waitcnt lgkmcnt(0)
	s_barrier
	s_waitcnt lgkmcnt(0)
	v_mfma_f32_16x16x32_bf16 v[60:63], v[146:149], v[178:181], v[60:63]
	v_mfma_f32_16x16x32_bf16 v[60:63], v[150:153], v[182:185], v[60:63]
	v_mfma_f32_16x16x32_bf16 v[48:51], v[154:157], v[178:181], v[48:51]
	v_mfma_f32_16x16x32_bf16 v[48:51], v[158:161], v[182:185], v[48:51]
	v_mfma_f32_16x16x32_bf16 v[56:59], v[162:165], v[178:181], v[56:59]
	v_mfma_f32_16x16x32_bf16 v[56:59], v[166:169], v[182:185], v[56:59]
	v_mfma_f32_16x16x32_bf16 v[52:55], v[170:173], v[178:181], v[52:55]
	v_mfma_f32_16x16x32_bf16 v[52:55], v[174:177], v[182:185], v[52:55]
	v_mfma_f32_16x16x32_bf16 v[36:39], v[170:173], v[186:189], v[36:39]
	v_mfma_f32_16x16x32_bf16 v[36:39], v[174:177], v[190:193], v[36:39]
	v_mfma_f32_16x16x32_bf16 v[40:43], v[162:165], v[186:189], v[40:43]
	v_mfma_f32_16x16x32_bf16 v[40:43], v[166:169], v[190:193], v[40:43]
	v_mfma_f32_16x16x32_bf16 v[32:35], v[154:157], v[186:189], v[32:35]
	v_mfma_f32_16x16x32_bf16 v[32:35], v[158:161], v[190:193], v[32:35]
	v_mfma_f32_16x16x32_bf16 v[44:47], v[146:149], v[186:189], v[44:47]
	v_mfma_f32_16x16x32_bf16 v[44:47], v[150:153], v[190:193], v[44:47]
	v_mfma_f32_16x16x32_bf16 v[28:31], v[146:149], v[194:197], v[28:31]
	v_mfma_f32_16x16x32_bf16 v[28:31], v[150:153], v[198:201], v[28:31]
	v_mfma_f32_16x16x32_bf16 v[16:19], v[154:157], v[194:197], v[16:19]
	v_mfma_f32_16x16x32_bf16 v[16:19], v[158:161], v[198:201], v[16:19]
	v_mfma_f32_16x16x32_bf16 v[24:27], v[162:165], v[194:197], v[24:27]
	v_mfma_f32_16x16x32_bf16 v[24:27], v[166:169], v[198:201], v[24:27]
	v_mfma_f32_16x16x32_bf16 v[20:23], v[170:173], v[194:197], v[20:23]
	v_mfma_f32_16x16x32_bf16 v[20:23], v[174:177], v[198:201], v[20:23]
	v_mfma_f32_16x16x32_bf16 v[4:7], v[170:173], v[202:205], v[4:7]
	v_mfma_f32_16x16x32_bf16 v[4:7], v[174:177], v[206:209], v[4:7]
	v_mfma_f32_16x16x32_bf16 v[8:11], v[162:165], v[202:205], v[8:11]
	v_mfma_f32_16x16x32_bf16 v[8:11], v[166:169], v[206:209], v[8:11]
	v_mfma_f32_16x16x32_bf16 v[0:3], v[154:157], v[202:205], v[0:3]
	v_mfma_f32_16x16x32_bf16 v[0:3], v[158:161], v[206:209], v[0:3]
	v_mfma_f32_16x16x32_bf16 v[12:15], v[146:149], v[202:205], v[12:15]
	v_mfma_f32_16x16x32_bf16 v[12:15], v[150:153], v[206:209], v[12:15]
	s_barrier
	s_mov_b32 m0, s57
	v_lshl_add_u64 v[216:217], v[214:215], 0, s[2:3]
	global_load_lds_dwordx4 v[216:217], off
	v_lshl_add_u64 v[216:217], v[214:215], 0, s[8:9]
	s_mov_b32 m0, s58
	s_nop 0
	global_load_lds_dwordx4 v[216:217], off
	ds_read_b128 v[146:149], v144
	ds_read_b128 v[150:153], v144 offset:1024
	ds_read_b128 v[154:157], v144 offset:2048
	ds_read_b128 v[158:161], v144 offset:3072
	ds_read_b128 v[162:165], v136
	ds_read_b128 v[166:169], v136 offset:1024
	ds_read_b128 v[170:173], v136 offset:2048
	ds_read_b128 v[174:177], v136 offset:3072
	ds_read_b128 v[178:181], v143 offset:32768
	ds_read_b128 v[182:185], v143 offset:33792
	ds_read_b128 v[186:189], v143 offset:34816
	ds_read_b128 v[190:193], v143 offset:35840
	ds_read_b128 v[194:197], v143 offset:36864
	ds_read_b128 v[198:201], v143 offset:37888
	ds_read_b128 v[202:205], v143 offset:38912
	ds_read_b128 v[206:209], v143 offset:39936
	s_waitcnt vmcnt(8)
	s_waitcnt lgkmcnt(0)
	s_barrier
	s_waitcnt lgkmcnt(0)
	v_mfma_f32_16x16x32_bf16 v[124:127], v[146:149], v[178:181], v[124:127]
	v_mfma_f32_16x16x32_bf16 v[124:127], v[150:153], v[182:185], v[124:127]
	v_mfma_f32_16x16x32_bf16 v[112:115], v[154:157], v[178:181], v[112:115]
	v_mfma_f32_16x16x32_bf16 v[112:115], v[158:161], v[182:185], v[112:115]
	v_mfma_f32_16x16x32_bf16 v[120:123], v[162:165], v[178:181], v[120:123]
	v_mfma_f32_16x16x32_bf16 v[120:123], v[166:169], v[182:185], v[120:123]
	v_mfma_f32_16x16x32_bf16 v[116:119], v[170:173], v[178:181], v[116:119]
	v_mfma_f32_16x16x32_bf16 v[116:119], v[174:177], v[182:185], v[116:119]
	v_mfma_f32_16x16x32_bf16 v[100:103], v[170:173], v[186:189], v[100:103]
	v_mfma_f32_16x16x32_bf16 v[100:103], v[174:177], v[190:193], v[100:103]
	v_mfma_f32_16x16x32_bf16 v[104:107], v[162:165], v[186:189], v[104:107]
	v_mfma_f32_16x16x32_bf16 v[104:107], v[166:169], v[190:193], v[104:107]
	v_mfma_f32_16x16x32_bf16 v[96:99], v[154:157], v[186:189], v[96:99]
	v_mfma_f32_16x16x32_bf16 v[96:99], v[158:161], v[190:193], v[96:99]
	v_mfma_f32_16x16x32_bf16 v[108:111], v[146:149], v[186:189], v[108:111]
	v_mfma_f32_16x16x32_bf16 v[108:111], v[150:153], v[190:193], v[108:111]
	v_mfma_f32_16x16x32_bf16 v[92:95], v[146:149], v[194:197], v[92:95]
	v_mfma_f32_16x16x32_bf16 v[92:95], v[150:153], v[198:201], v[92:95]
	v_mfma_f32_16x16x32_bf16 v[80:83], v[154:157], v[194:197], v[80:83]
	v_mfma_f32_16x16x32_bf16 v[80:83], v[158:161], v[198:201], v[80:83]
	v_mfma_f32_16x16x32_bf16 v[88:91], v[162:165], v[194:197], v[88:91]
	v_mfma_f32_16x16x32_bf16 v[88:91], v[166:169], v[198:201], v[88:91]
	v_mfma_f32_16x16x32_bf16 v[84:87], v[170:173], v[194:197], v[84:87]
	v_mfma_f32_16x16x32_bf16 v[84:87], v[174:177], v[198:201], v[84:87]
	v_mfma_f32_16x16x32_bf16 v[68:71], v[170:173], v[202:205], v[68:71]
	v_mfma_f32_16x16x32_bf16 v[68:71], v[174:177], v[206:209], v[68:71]
	v_mfma_f32_16x16x32_bf16 v[72:75], v[162:165], v[202:205], v[72:75]
	v_mfma_f32_16x16x32_bf16 v[72:75], v[166:169], v[206:209], v[72:75]
	v_mfma_f32_16x16x32_bf16 v[64:67], v[154:157], v[202:205], v[64:67]
	v_mfma_f32_16x16x32_bf16 v[64:67], v[158:161], v[206:209], v[64:67]
	v_mfma_f32_16x16x32_bf16 v[76:79], v[146:149], v[202:205], v[76:79]
	v_mfma_f32_16x16x32_bf16 v[76:79], v[150:153], v[206:209], v[76:79]
	s_barrier
	s_mov_b32 m0, s77
	v_lshl_add_u64 v[216:217], v[212:213], 0, s[18:19]
	global_load_lds_dwordx4 v[216:217], off
	v_lshl_add_u64 v[216:217], v[212:213], 0, s[20:21]
	s_mov_b32 m0, s78
	s_nop 0
	global_load_lds_dwordx4 v[216:217], off
	v_lshl_add_u64 v[216:217], v[212:213], 0, s[22:23]
	s_mov_b32 m0, s79
	v_lshl_add_u64 v[212:213], v[212:213], 0, s[24:25]
	global_load_lds_dwordx4 v[216:217], off
	s_mov_b32 m0, s80
	s_nop 0
	global_load_lds_dwordx4 v[212:213], off
	v_lshl_add_u64 v[212:213], v[214:215], 0, s[18:19]
	s_mov_b32 m0, s60
	s_nop 0
	global_load_lds_dwordx4 v[212:213], off
	v_lshl_add_u64 v[212:213], v[214:215], 0, s[20:21]
	s_mov_b32 m0, s61
	s_nop 0
	global_load_lds_dwordx4 v[212:213], off
	ds_read_b128 v[178:181], v143 offset:49152
	ds_read_b128 v[182:185], v143 offset:50176
	ds_read_b128 v[186:189], v143 offset:51200
	ds_read_b128 v[190:193], v143 offset:52224
	ds_read_b128 v[194:197], v143 offset:53248
	ds_read_b128 v[198:201], v143 offset:54272
	ds_read_b128 v[202:205], v143 offset:55296
	ds_read_b128 v[206:209], v143 offset:56320
	s_waitcnt vmcnt(8)
	s_waitcnt lgkmcnt(0)
	s_barrier
	s_waitcnt lgkmcnt(0)
	v_mfma_f32_16x16x32_bf16 v[60:63], v[146:149], v[178:181], v[60:63]
	v_mfma_f32_16x16x32_bf16 v[60:63], v[150:153], v[182:185], v[60:63]
	v_mfma_f32_16x16x32_bf16 v[48:51], v[154:157], v[178:181], v[48:51]
	v_mfma_f32_16x16x32_bf16 v[48:51], v[158:161], v[182:185], v[48:51]
	v_mfma_f32_16x16x32_bf16 v[56:59], v[162:165], v[178:181], v[56:59]
	v_mfma_f32_16x16x32_bf16 v[56:59], v[166:169], v[182:185], v[56:59]
	v_mfma_f32_16x16x32_bf16 v[52:55], v[170:173], v[178:181], v[52:55]
	v_mfma_f32_16x16x32_bf16 v[52:55], v[174:177], v[182:185], v[52:55]
	v_mfma_f32_16x16x32_bf16 v[36:39], v[170:173], v[186:189], v[36:39]
	v_mfma_f32_16x16x32_bf16 v[36:39], v[174:177], v[190:193], v[36:39]
	v_mfma_f32_16x16x32_bf16 v[40:43], v[162:165], v[186:189], v[40:43]
	v_mfma_f32_16x16x32_bf16 v[40:43], v[166:169], v[190:193], v[40:43]
	v_mfma_f32_16x16x32_bf16 v[32:35], v[154:157], v[186:189], v[32:35]
	v_mfma_f32_16x16x32_bf16 v[32:35], v[158:161], v[190:193], v[32:35]
	v_mfma_f32_16x16x32_bf16 v[44:47], v[146:149], v[186:189], v[44:47]
	v_mfma_f32_16x16x32_bf16 v[44:47], v[150:153], v[190:193], v[44:47]
	v_mfma_f32_16x16x32_bf16 v[28:31], v[146:149], v[194:197], v[28:31]
	v_mfma_f32_16x16x32_bf16 v[28:31], v[150:153], v[198:201], v[28:31]
	v_mfma_f32_16x16x32_bf16 v[16:19], v[154:157], v[194:197], v[16:19]
	v_mfma_f32_16x16x32_bf16 v[16:19], v[158:161], v[198:201], v[16:19]
	v_mfma_f32_16x16x32_bf16 v[24:27], v[162:165], v[194:197], v[24:27]
	v_mfma_f32_16x16x32_bf16 v[24:27], v[166:169], v[198:201], v[24:27]
	v_mfma_f32_16x16x32_bf16 v[20:23], v[170:173], v[194:197], v[20:23]
	v_mfma_f32_16x16x32_bf16 v[20:23], v[174:177], v[198:201], v[20:23]
	v_mfma_f32_16x16x32_bf16 v[4:7], v[170:173], v[202:205], v[4:7]
	v_mfma_f32_16x16x32_bf16 v[4:7], v[174:177], v[206:209], v[4:7]
	v_mfma_f32_16x16x32_bf16 v[8:11], v[162:165], v[202:205], v[8:11]
	v_mfma_f32_16x16x32_bf16 v[8:11], v[166:169], v[206:209], v[8:11]
	v_mfma_f32_16x16x32_bf16 v[0:3], v[154:157], v[202:205], v[0:3]
	v_mfma_f32_16x16x32_bf16 v[0:3], v[158:161], v[206:209], v[0:3]
	v_mfma_f32_16x16x32_bf16 v[12:15], v[146:149], v[202:205], v[12:15]
	v_mfma_f32_16x16x32_bf16 v[12:15], v[150:153], v[206:209], v[12:15]
	s_barrier
	s_cmp_gt_u32 s29, 13
	s_cbranch_scc0 .LBB0_175
	s_and_b64 vcc, exec, s[26:27]
	s_cbranch_vccz .LBB0_178
	s_barrier

.LBB0_255:
	s_add_i32 s73, s73, 2
	s_mov_b32 s74, s73
	s_ashr_i32 s75, s74, 31
	s_lshl_b64 s[76:77], s[74:75], 7
	s_add_u32 s75, s76, 0x100
	s_addc_u32 s78, s77, 0
	s_add_u32 s79, s40, s75
	s_addc_u32 s80, s41, s78
	s_add_u32 s81, s38, s75
	s_addc_u32 s78, s39, s78
	s_cmp_eq_u32 s74, 42
	s_cselect_b32 s75, s1, s80
	s_cselect_b32 s74, s0, s79
	s_cselect_b32 s79, s43, s78
	s_cselect_b32 s78, s42, s81
	v_lshl_add_u64 v[208:209], v[136:137], 0, s[76:77]
	v_lshl_add_u64 v[212:213], v[208:209], 0, s[20:21]
	s_add_i32 m0, s53, 0xc000
	s_nop 0
	global_load_lds_dwordx4 v[212:213], off
	v_lshl_add_u64 v[208:209], v[208:209], 0, s[22:23]
	s_add_i32 m0, s53, 0xe000
	s_nop 0
	global_load_lds_dwordx4 v[208:209], off
	ds_read_b128 v[144:147], v141
	ds_read_b128 v[148:151], v141 offset:1024
	ds_read_b128 v[152:155], v141 offset:2048
	ds_read_b128 v[156:159], v141 offset:3072
	ds_read_b128 v[160:163], v142
	ds_read_b128 v[164:167], v142 offset:1024
	ds_read_b128 v[168:171], v142 offset:2048
	ds_read_b128 v[172:175], v142 offset:3072
	ds_read_b128 v[176:179], v143
	ds_read_b128 v[180:183], v143 offset:1024
	ds_read_b128 v[184:187], v143 offset:2048
	ds_read_b128 v[188:191], v143 offset:3072
	ds_read_b128 v[192:195], v143 offset:4096
	ds_read_b128 v[196:199], v143 offset:5120
	ds_read_b128 v[200:203], v143 offset:6144
	ds_read_b128 v[204:207], v143 offset:7168
	s_waitcnt vmcnt(8)
	s_waitcnt lgkmcnt(0)
	s_barrier
	s_waitcnt lgkmcnt(0)
	v_mfma_f32_16x16x32_bf16 v[124:127], v[144:147], v[176:179], v[124:127]
	v_mfma_f32_16x16x32_bf16 v[124:127], v[148:151], v[180:183], v[124:127]
	v_mfma_f32_16x16x32_bf16 v[120:123], v[152:155], v[176:179], v[120:123]
	v_mfma_f32_16x16x32_bf16 v[120:123], v[156:159], v[180:183], v[120:123]
	v_mfma_f32_16x16x32_bf16 v[108:111], v[160:163], v[176:179], v[108:111]
	v_mfma_f32_16x16x32_bf16 v[108:111], v[164:167], v[180:183], v[108:111]
	v_mfma_f32_16x16x32_bf16 v[104:107], v[168:171], v[176:179], v[104:107]
	v_mfma_f32_16x16x32_bf16 v[104:107], v[172:175], v[180:183], v[104:107]
	v_mfma_f32_16x16x32_bf16 v[88:91], v[168:171], v[184:187], v[88:91]
	v_mfma_f32_16x16x32_bf16 v[88:91], v[172:175], v[188:191], v[88:91]
	v_mfma_f32_16x16x32_bf16 v[92:95], v[160:163], v[184:187], v[92:95]
	v_mfma_f32_16x16x32_bf16 v[92:95], v[164:167], v[188:191], v[92:95]
	v_mfma_f32_16x16x32_bf16 v[112:115], v[152:155], v[184:187], v[112:115]
	v_mfma_f32_16x16x32_bf16 v[112:115], v[156:159], v[188:191], v[112:115]
	v_mfma_f32_16x16x32_bf16 v[116:119], v[144:147], v[184:187], v[116:119]
	v_mfma_f32_16x16x32_bf16 v[116:119], v[148:151], v[188:191], v[116:119]
	v_mfma_f32_16x16x32_bf16 v[100:103], v[144:147], v[192:195], v[100:103]
	v_mfma_f32_16x16x32_bf16 v[100:103], v[148:151], v[196:199], v[100:103]
	v_mfma_f32_16x16x32_bf16 v[96:99], v[152:155], v[192:195], v[96:99]
	v_mfma_f32_16x16x32_bf16 v[96:99], v[156:159], v[196:199], v[96:99]
	v_mfma_f32_16x16x32_bf16 v[76:79], v[160:163], v[192:195], v[76:79]
	v_mfma_f32_16x16x32_bf16 v[76:79], v[164:167], v[196:199], v[76:79]
	v_mfma_f32_16x16x32_bf16 v[72:75], v[168:171], v[192:195], v[72:75]
	v_mfma_f32_16x16x32_bf16 v[72:75], v[172:175], v[196:199], v[72:75]
	v_mfma_f32_16x16x32_bf16 v[64:67], v[168:171], v[200:203], v[64:67]
	v_mfma_f32_16x16x32_bf16 v[64:67], v[172:175], v[204:207], v[64:67]
	v_mfma_f32_16x16x32_bf16 v[68:71], v[160:163], v[200:203], v[68:71]
	v_mfma_f32_16x16x32_bf16 v[68:71], v[164:167], v[204:207], v[68:71]
	v_mfma_f32_16x16x32_bf16 v[80:83], v[152:155], v[200:203], v[80:83]
	v_mfma_f32_16x16x32_bf16 v[80:83], v[156:159], v[204:207], v[80:83]
	v_mfma_f32_16x16x32_bf16 v[84:87], v[144:147], v[200:203], v[84:87]
	v_mfma_f32_16x16x32_bf16 v[84:87], v[148:151], v[204:207], v[84:87]
	s_barrier
	s_add_i32 s76, s63, s52
	v_lshl_add_u64 v[208:209], s[78:79], 0, v[130:131]
	s_mov_b32 m0, s76
	s_nop 0
	global_load_lds_dwordx4 v[208:209], off
	v_lshl_add_u64 v[212:213], v[208:209], 0, s[2:3]
	s_add_i32 m0, s76, 0x2000
	s_add_i32 s76, s64, s52
	global_load_lds_dwordx4 v[212:213], off
	v_lshl_add_u64 v[212:213], v[208:209], 0, s[8:9]
	s_mov_b32 m0, s76
	s_nop 0
	global_load_lds_dwordx4 v[212:213], off
	v_lshl_add_u64 v[212:213], v[208:209], 0, s[14:15]
	s_add_i32 m0, s76, 0x2000
	s_nop 0
	global_load_lds_dwordx4 v[212:213], off
	v_lshl_add_u64 v[212:213], s[74:75], 0, v[128:129]
	s_mov_b32 m0, s53
	v_lshl_add_u64 v[214:215], v[212:213], 0, s[2:3]
	global_load_lds_dwordx4 v[212:213], off
	s_mov_b32 m0, s54
	s_nop 0
	global_load_lds_dwordx4 v[214:215], off
	ds_read_b128 v[176:179], v143 offset:16384
	ds_read_b128 v[180:183], v143 offset:17408
	ds_read_b128 v[184:187], v143 offset:18432
	ds_read_b128 v[188:191], v143 offset:19456
	ds_read_b128 v[192:195], v143 offset:20480
	ds_read_b128 v[196:199], v143 offset:21504
	ds_read_b128 v[200:203], v143 offset:22528
	ds_read_b128 v[204:207], v143 offset:23552
	s_waitcnt vmcnt(8)
	s_waitcnt lgkmcnt(0)
	s_barrier
	s_waitcnt lgkmcnt(0)
	v_mfma_f32_16x16x32_bf16 v[60:63], v[144:147], v[176:179], v[60:63]
	v_mfma_f32_16x16x32_bf16 v[60:63], v[148:151], v[180:183], v[60:63]
	v_mfma_f32_16x16x32_bf16 v[56:59], v[152:155], v[176:179], v[56:59]
	v_mfma_f32_16x16x32_bf16 v[56:59], v[156:159], v[180:183], v[56:59]
	v_mfma_f32_16x16x32_bf16 v[44:47], v[160:163], v[176:179], v[44:47]
	v_mfma_f32_16x16x32_bf16 v[44:47], v[164:167], v[180:183], v[44:47]
	v_mfma_f32_16x16x32_bf16 v[40:43], v[168:171], v[176:179], v[40:43]
	v_mfma_f32_16x16x32_bf16 v[40:43], v[172:175], v[180:183], v[40:43]
	v_mfma_f32_16x16x32_bf16 v[24:27], v[168:171], v[184:187], v[24:27]
	v_mfma_f32_16x16x32_bf16 v[24:27], v[172:175], v[188:191], v[24:27]
	v_mfma_f32_16x16x32_bf16 v[28:31], v[160:163], v[184:187], v[28:31]
	v_mfma_f32_16x16x32_bf16 v[28:31], v[164:167], v[188:191], v[28:31]
	v_mfma_f32_16x16x32_bf16 v[48:51], v[152:155], v[184:187], v[48:51]
	v_mfma_f32_16x16x32_bf16 v[48:51], v[156:159], v[188:191], v[48:51]
	v_mfma_f32_16x16x32_bf16 v[52:55], v[144:147], v[184:187], v[52:55]
	v_mfma_f32_16x16x32_bf16 v[52:55], v[148:151], v[188:191], v[52:55]
	v_mfma_f32_16x16x32_bf16 v[36:39], v[144:147], v[192:195], v[36:39]
	v_mfma_f32_16x16x32_bf16 v[36:39], v[148:151], v[196:199], v[36:39]
	v_mfma_f32_16x16x32_bf16 v[32:35], v[152:155], v[192:195], v[32:35]
	v_mfma_f32_16x16x32_bf16 v[32:35], v[156:159], v[196:199], v[32:35]
	v_mfma_f32_16x16x32_bf16 v[12:15], v[160:163], v[192:195], v[12:15]
	v_mfma_f32_16x16x32_bf16 v[12:15], v[164:167], v[196:199], v[12:15]
	v_mfma_f32_16x16x32_bf16 v[8:11], v[168:171], v[192:195], v[8:11]
	v_mfma_f32_16x16x32_bf16 v[8:11], v[172:175], v[196:199], v[8:11]
	v_mfma_f32_16x16x32_bf16 v[0:3], v[168:171], v[200:203], v[0:3]
	v_mfma_f32_16x16x32_bf16 v[0:3], v[172:175], v[204:207], v[0:3]
	v_mfma_f32_16x16x32_bf16 v[4:7], v[160:163], v[200:203], v[4:7]
	v_mfma_f32_16x16x32_bf16 v[4:7], v[164:167], v[204:207], v[4:7]
	v_mfma_f32_16x16x32_bf16 v[16:19], v[152:155], v[200:203], v[16:19]
	v_mfma_f32_16x16x32_bf16 v[16:19], v[156:159], v[204:207], v[16:19]
	v_mfma_f32_16x16x32_bf16 v[20:23], v[144:147], v[200:203], v[20:23]
	v_mfma_f32_16x16x32_bf16 v[20:23], v[148:151], v[204:207], v[20:23]
	s_barrier
	s_add_i32 s74, 0, 0x18000
	s_add_i32 s75, 0, 0x1c000
	v_add_u32_e32 v156, s74, v140
	v_add_u32_e32 v172, s75, v140
	s_mov_b32 m0, s55
	v_lshl_add_u64 v[214:215], v[212:213], 0, s[8:9]
	global_load_lds_dwordx4 v[214:215], off
	v_lshl_add_u64 v[214:215], v[212:213], 0, s[14:15]
	s_mov_b32 m0, s56
	s_nop 0
	global_load_lds_dwordx4 v[214:215], off
	ds_read_b128 v[144:147], v156
	ds_read_b128 v[148:151], v156 offset:1024
	ds_read_b128 v[152:155], v156 offset:2048
	ds_read_b128 v[156:159], v156 offset:3072
	ds_read_b128 v[160:163], v172
	ds_read_b128 v[164:167], v172 offset:1024
	ds_read_b128 v[168:171], v172 offset:2048
	ds_read_b128 v[172:175], v172 offset:3072
	ds_read_b128 v[176:179], v143 offset:32768
	ds_read_b128 v[180:183], v143 offset:33792
	ds_read_b128 v[184:187], v143 offset:34816
	ds_read_b128 v[188:191], v143 offset:35840
	ds_read_b128 v[192:195], v143 offset:36864
	ds_read_b128 v[196:199], v143 offset:37888
	ds_read_b128 v[200:203], v143 offset:38912
	ds_read_b128 v[204:207], v143 offset:39936
	s_waitcnt vmcnt(8)
	s_waitcnt lgkmcnt(0)
	s_barrier
	s_waitcnt lgkmcnt(0)
	v_mfma_f32_16x16x32_bf16 v[124:127], v[144:147], v[176:179], v[124:127]
	v_mfma_f32_16x16x32_bf16 v[124:127], v[148:151], v[180:183], v[124:127]
	v_mfma_f32_16x16x32_bf16 v[120:123], v[152:155], v[176:179], v[120:123]
	v_mfma_f32_16x16x32_bf16 v[120:123], v[156:159], v[180:183], v[120:123]
	v_mfma_f32_16x16x32_bf16 v[108:111], v[160:163], v[176:179], v[108:111]
	v_mfma_f32_16x16x32_bf16 v[108:111], v[164:167], v[180:183], v[108:111]
	v_mfma_f32_16x16x32_bf16 v[104:107], v[168:171], v[176:179], v[104:107]
	v_mfma_f32_16x16x32_bf16 v[104:107], v[172:175], v[180:183], v[104:107]
	v_mfma_f32_16x16x32_bf16 v[88:91], v[168:171], v[184:187], v[88:91]
	v_mfma_f32_16x16x32_bf16 v[88:91], v[172:175], v[188:191], v[88:91]
	v_mfma_f32_16x16x32_bf16 v[92:95], v[160:163], v[184:187], v[92:95]
	v_mfma_f32_16x16x32_bf16 v[92:95], v[164:167], v[188:191], v[92:95]
	v_mfma_f32_16x16x32_bf16 v[112:115], v[152:155], v[184:187], v[112:115]
	v_mfma_f32_16x16x32_bf16 v[112:115], v[156:159], v[188:191], v[112:115]
	v_mfma_f32_16x16x32_bf16 v[116:119], v[144:147], v[184:187], v[116:119]
	v_mfma_f32_16x16x32_bf16 v[116:119], v[148:151], v[188:191], v[116:119]
	v_mfma_f32_16x16x32_bf16 v[100:103], v[144:147], v[192:195], v[100:103]
	v_mfma_f32_16x16x32_bf16 v[100:103], v[148:151], v[196:199], v[100:103]
	v_mfma_f32_16x16x32_bf16 v[96:99], v[152:155], v[192:195], v[96:99]
	v_mfma_f32_16x16x32_bf16 v[96:99], v[156:159], v[196:199], v[96:99]
	v_mfma_f32_16x16x32_bf16 v[76:79], v[160:163], v[192:195], v[76:79]
	v_mfma_f32_16x16x32_bf16 v[76:79], v[164:167], v[196:199], v[76:79]
	v_mfma_f32_16x16x32_bf16 v[72:75], v[168:171], v[192:195], v[72:75]
	v_mfma_f32_16x16x32_bf16 v[72:75], v[172:175], v[196:199], v[72:75]
	v_mfma_f32_16x16x32_bf16 v[64:67], v[168:171], v[200:203], v[64:67]
	v_mfma_f32_16x16x32_bf16 v[64:67], v[172:175], v[204:207], v[64:67]
	v_mfma_f32_16x16x32_bf16 v[68:71], v[160:163], v[200:203], v[68:71]
	v_mfma_f32_16x16x32_bf16 v[68:71], v[164:167], v[204:207], v[68:71]
	v_mfma_f32_16x16x32_bf16 v[80:83], v[152:155], v[200:203], v[80:83]
	v_mfma_f32_16x16x32_bf16 v[80:83], v[156:159], v[204:207], v[80:83]
	v_mfma_f32_16x16x32_bf16 v[84:87], v[144:147], v[200:203], v[84:87]
	v_mfma_f32_16x16x32_bf16 v[84:87], v[148:151], v[204:207], v[84:87]
	s_barrier
	s_add_i32 s74, s74, s52
	v_lshl_add_u64 v[214:215], v[208:209], 0, s[20:21]
	s_mov_b32 m0, s74
	s_nop 0
	global_load_lds_dwordx4 v[214:215], off
	v_lshl_add_u64 v[214:215], v[208:209], 0, s[22:23]
	s_add_i32 m0, s74, 0x2000
	s_add_i32 s74, s75, s52
	global_load_lds_dwordx4 v[214:215], off
	v_lshl_add_u64 v[214:215], v[208:209], 0, s[24:25]
	s_mov_b32 m0, s74
	v_lshl_add_u64 v[208:209], v[208:209], 0, s[26:27]
	global_load_lds_dwordx4 v[214:215], off
	s_add_i32 m0, s74, 0x2000
	s_nop 0
	global_load_lds_dwordx4 v[208:209], off
	v_lshl_add_u64 v[208:209], v[212:213], 0, s[20:21]
	s_mov_b32 m0, s58
	s_nop 0
	global_load_lds_dwordx4 v[208:209], off
	v_lshl_add_u64 v[208:209], v[212:213], 0, s[22:23]
	s_mov_b32 m0, s59
	s_nop 0
	global_load_lds_dwordx4 v[208:209], off
	ds_read_b128 v[176:179], v143 offset:49152
	ds_read_b128 v[180:183], v143 offset:50176
	ds_read_b128 v[184:187], v143 offset:51200
	ds_read_b128 v[188:191], v143 offset:52224
	ds_read_b128 v[192:195], v143 offset:53248
	ds_read_b128 v[196:199], v143 offset:54272
	ds_read_b128 v[200:203], v143 offset:55296
	ds_read_b128 v[204:207], v143 offset:56320
	s_waitcnt vmcnt(8)
	s_waitcnt lgkmcnt(0)
	s_barrier
	s_waitcnt lgkmcnt(0)
	v_mfma_f32_16x16x32_bf16 v[60:63], v[144:147], v[176:179], v[60:63]
	v_mfma_f32_16x16x32_bf16 v[60:63], v[148:151], v[180:183], v[60:63]
	v_mfma_f32_16x16x32_bf16 v[56:59], v[152:155], v[176:179], v[56:59]
	v_mfma_f32_16x16x32_bf16 v[56:59], v[156:159], v[180:183], v[56:59]
	v_mfma_f32_16x16x32_bf16 v[44:47], v[160:163], v[176:179], v[44:47]
	v_mfma_f32_16x16x32_bf16 v[44:47], v[164:167], v[180:183], v[44:47]
	v_mfma_f32_16x16x32_bf16 v[40:43], v[168:171], v[176:179], v[40:43]
	v_mfma_f32_16x16x32_bf16 v[40:43], v[172:175], v[180:183], v[40:43]
	v_mfma_f32_16x16x32_bf16 v[24:27], v[168:171], v[184:187], v[24:27]
	v_mfma_f32_16x16x32_bf16 v[24:27], v[172:175], v[188:191], v[24:27]
	v_mfma_f32_16x16x32_bf16 v[28:31], v[160:163], v[184:187], v[28:31]
	v_mfma_f32_16x16x32_bf16 v[28:31], v[164:167], v[188:191], v[28:31]
	v_mfma_f32_16x16x32_bf16 v[48:51], v[152:155], v[184:187], v[48:51]
	v_mfma_f32_16x16x32_bf16 v[48:51], v[156:159], v[188:191], v[48:51]
	v_mfma_f32_16x16x32_bf16 v[52:55], v[144:147], v[184:187], v[52:55]
	v_mfma_f32_16x16x32_bf16 v[52:55], v[148:151], v[188:191], v[52:55]
	v_mfma_f32_16x16x32_bf16 v[36:39], v[144:147], v[192:195], v[36:39]
	v_mfma_f32_16x16x32_bf16 v[36:39], v[148:151], v[196:199], v[36:39]
	v_mfma_f32_16x16x32_bf16 v[32:35], v[152:155], v[192:195], v[32:35]
	v_mfma_f32_16x16x32_bf16 v[32:35], v[156:159], v[196:199], v[32:35]
	v_mfma_f32_16x16x32_bf16 v[12:15], v[160:163], v[192:195], v[12:15]
	v_mfma_f32_16x16x32_bf16 v[12:15], v[164:167], v[196:199], v[12:15]
	v_mfma_f32_16x16x32_bf16 v[8:11], v[168:171], v[192:195], v[8:11]
	v_mfma_f32_16x16x32_bf16 v[8:11], v[172:175], v[196:199], v[8:11]
	v_mfma_f32_16x16x32_bf16 v[0:3], v[168:171], v[200:203], v[0:3]
	v_mfma_f32_16x16x32_bf16 v[0:3], v[172:175], v[204:207], v[0:3]
	v_mfma_f32_16x16x32_bf16 v[4:7], v[160:163], v[200:203], v[4:7]
	v_mfma_f32_16x16x32_bf16 v[4:7], v[164:167], v[204:207], v[4:7]
	v_mfma_f32_16x16x32_bf16 v[16:19], v[152:155], v[200:203], v[16:19]
	v_mfma_f32_16x16x32_bf16 v[16:19], v[156:159], v[204:207], v[16:19]
	v_mfma_f32_16x16x32_bf16 v[20:23], v[144:147], v[200:203], v[20:23]
	v_mfma_f32_16x16x32_bf16 v[20:23], v[148:151], v[204:207], v[20:23]
	s_barrier
	s_cmp_gt_u32 s73, 41
	s_cbranch_scc0 .LBB0_255
	s_and_b64 vcc, exec, s[28:29]
	s_cbranch_vccz .LBB0_258
	s_barrier

.LBB0_386:
	s_add_i32 s70, s70, 2
	s_mov_b32 s42, s70
	s_ashr_i32 s43, s42, 31
	s_lshl_b64 s[72:73], s[42:43], 7
	s_add_u32 s43, s72, 0x100
	s_addc_u32 s71, s73, 0
	s_add_u32 s79, s8, s43
	s_addc_u32 s80, s9, s71
	s_add_u32 s82, s2, s43
	s_addc_u32 s71, s3, s71
	s_add_i32 s83, 0, 0x10000
	s_cmp_eq_u32 s42, 14
	s_cselect_b32 s43, s1, s80
	s_cselect_b32 s42, s57, s79
	s_cselect_b32 s81, s68, s71
	s_cselect_b32 s80, s69, s82
	s_add_i32 s71, 0, 0x14000
	v_add_u32_e32 v140, s83, v220
	v_add_u32_e32 v156, s71, v220
	s_add_u32 s72, s8, s72
	s_addc_u32 s73, s9, s73
	v_lshl_add_u64 v[222:223], s[72:73], 0, v[182:183]
	v_lshl_add_u64 v[224:225], v[222:223], 0, s[14:15]
	s_add_i32 m0, s39, 0xc000
	s_nop 0
	global_load_lds_dwordx4 v[224:225], off
	v_lshl_add_u64 v[222:223], v[222:223], 0, s[16:17]
	s_add_i32 m0, s39, 0xe000
	s_nop 0
	global_load_lds_dwordx4 v[222:223], off
	ds_read_b128 v[128:131], v140
	ds_read_b128 v[132:135], v140 offset:1024
	ds_read_b128 v[136:139], v140 offset:2048
	ds_read_b128 v[140:143], v140 offset:3072
	ds_read_b128 v[144:147], v156
	ds_read_b128 v[148:151], v156 offset:1024
	ds_read_b128 v[152:155], v156 offset:2048
	ds_read_b128 v[156:159], v156 offset:3072
	ds_read_b128 v[160:163], v221
	ds_read_b128 v[164:167], v221 offset:1024
	ds_read_b128 v[186:189], v221 offset:2048
	ds_read_b128 v[190:193], v221 offset:3072
	ds_read_b128 v[194:197], v221 offset:4096
	ds_read_b128 v[198:201], v221 offset:5120
	ds_read_b128 v[202:205], v221 offset:6144
	ds_read_b128 v[206:209], v221 offset:7168
	s_waitcnt vmcnt(8)
	s_waitcnt lgkmcnt(0)
	s_barrier
	s_waitcnt lgkmcnt(0)
	v_mfma_f32_16x16x32_bf16 v[124:127], v[128:131], v[160:163], v[124:127]
	v_mfma_f32_16x16x32_bf16 v[124:127], v[132:135], v[164:167], v[124:127]
	v_mfma_f32_16x16x32_bf16 v[120:123], v[136:139], v[160:163], v[120:123]
	v_mfma_f32_16x16x32_bf16 v[120:123], v[140:143], v[164:167], v[120:123]
	v_mfma_f32_16x16x32_bf16 v[116:119], v[144:147], v[160:163], v[116:119]
	v_mfma_f32_16x16x32_bf16 v[116:119], v[148:151], v[164:167], v[116:119]
	v_mfma_f32_16x16x32_bf16 v[108:111], v[152:155], v[160:163], v[108:111]
	v_mfma_f32_16x16x32_bf16 v[108:111], v[156:159], v[164:167], v[108:111]
	v_mfma_f32_16x16x32_bf16 v[92:95], v[152:155], v[186:189], v[92:95]
	v_mfma_f32_16x16x32_bf16 v[92:95], v[156:159], v[190:193], v[92:95]
	v_mfma_f32_16x16x32_bf16 v[100:103], v[144:147], v[186:189], v[100:103]
	v_mfma_f32_16x16x32_bf16 v[100:103], v[148:151], v[190:193], v[100:103]
	v_mfma_f32_16x16x32_bf16 v[104:107], v[136:139], v[186:189], v[104:107]
	v_mfma_f32_16x16x32_bf16 v[104:107], v[140:143], v[190:193], v[104:107]
	v_mfma_f32_16x16x32_bf16 v[112:115], v[128:131], v[186:189], v[112:115]
	v_mfma_f32_16x16x32_bf16 v[112:115], v[132:135], v[190:193], v[112:115]
	v_mfma_f32_16x16x32_bf16 v[96:99], v[128:131], v[194:197], v[96:99]
	v_mfma_f32_16x16x32_bf16 v[96:99], v[132:135], v[198:201], v[96:99]
	v_mfma_f32_16x16x32_bf16 v[88:91], v[136:139], v[194:197], v[88:91]
	v_mfma_f32_16x16x32_bf16 v[88:91], v[140:143], v[198:201], v[88:91]
	v_mfma_f32_16x16x32_bf16 v[84:87], v[144:147], v[194:197], v[84:87]
	v_mfma_f32_16x16x32_bf16 v[84:87], v[148:151], v[198:201], v[84:87]
	v_mfma_f32_16x16x32_bf16 v[76:79], v[152:155], v[194:197], v[76:79]
	v_mfma_f32_16x16x32_bf16 v[76:79], v[156:159], v[198:201], v[76:79]
	v_mfma_f32_16x16x32_bf16 v[64:67], v[152:155], v[202:205], v[64:67]
	v_mfma_f32_16x16x32_bf16 v[64:67], v[156:159], v[206:209], v[64:67]
	v_mfma_f32_16x16x32_bf16 v[68:71], v[144:147], v[202:205], v[68:71]
	v_mfma_f32_16x16x32_bf16 v[68:71], v[148:151], v[206:209], v[68:71]
	v_mfma_f32_16x16x32_bf16 v[72:75], v[136:139], v[202:205], v[72:75]
	v_mfma_f32_16x16x32_bf16 v[72:75], v[140:143], v[206:209], v[72:75]
	v_mfma_f32_16x16x32_bf16 v[80:83], v[128:131], v[202:205], v[80:83]
	v_mfma_f32_16x16x32_bf16 v[80:83], v[132:135], v[206:209], v[80:83]
	s_barrier
	s_add_i32 s72, s83, s74
	v_lshl_add_u64 v[222:223], s[80:81], 0, v[184:185]
	s_mov_b32 m0, s72
	s_nop 0
	global_load_lds_dwordx4 v[222:223], off
	v_lshl_add_u64 v[224:225], v[222:223], 0, s[40:41]
	s_add_i32 m0, s72, 0x2000
	s_add_i32 s71, s71, s74
	global_load_lds_dwordx4 v[224:225], off
	v_lshl_add_u64 v[224:225], v[222:223], 0, s[4:5]
	s_mov_b32 m0, s71
	s_nop 0
	global_load_lds_dwordx4 v[224:225], off
	v_lshl_add_u64 v[224:225], v[222:223], 0, s[6:7]
	s_add_i32 m0, s71, 0x2000
	s_nop 0
	global_load_lds_dwordx4 v[224:225], off
	v_lshl_add_u64 v[224:225], s[42:43], 0, v[182:183]
	s_mov_b32 m0, s39
	v_lshl_add_u64 v[226:227], v[224:225], 0, s[40:41]
	global_load_lds_dwordx4 v[224:225], off
	s_mov_b32 m0, s75
	s_nop 0
	global_load_lds_dwordx4 v[226:227], off
	ds_read_b128 v[160:163], v221 offset:16384
	ds_read_b128 v[164:167], v221 offset:17408
	ds_read_b128 v[186:189], v221 offset:18432
	ds_read_b128 v[190:193], v221 offset:19456
	ds_read_b128 v[194:197], v221 offset:20480
	ds_read_b128 v[198:201], v221 offset:21504
	ds_read_b128 v[202:205], v221 offset:22528
	ds_read_b128 v[206:209], v221 offset:23552
	s_waitcnt vmcnt(8)
	s_waitcnt lgkmcnt(0)
	s_barrier
	s_waitcnt lgkmcnt(0)
	v_mfma_f32_16x16x32_bf16 v[60:63], v[128:131], v[160:163], v[60:63]
	v_mfma_f32_16x16x32_bf16 v[60:63], v[132:135], v[164:167], v[60:63]
	v_mfma_f32_16x16x32_bf16 v[56:59], v[136:139], v[160:163], v[56:59]
	v_mfma_f32_16x16x32_bf16 v[56:59], v[140:143], v[164:167], v[56:59]
	v_mfma_f32_16x16x32_bf16 v[52:55], v[144:147], v[160:163], v[52:55]
	v_mfma_f32_16x16x32_bf16 v[52:55], v[148:151], v[164:167], v[52:55]
	v_mfma_f32_16x16x32_bf16 v[44:47], v[152:155], v[160:163], v[44:47]
	v_mfma_f32_16x16x32_bf16 v[44:47], v[156:159], v[164:167], v[44:47]
	v_mfma_f32_16x16x32_bf16 v[28:31], v[152:155], v[186:189], v[28:31]
	v_mfma_f32_16x16x32_bf16 v[28:31], v[156:159], v[190:193], v[28:31]
	v_mfma_f32_16x16x32_bf16 v[36:39], v[144:147], v[186:189], v[36:39]
	v_mfma_f32_16x16x32_bf16 v[36:39], v[148:151], v[190:193], v[36:39]
	v_mfma_f32_16x16x32_bf16 v[40:43], v[136:139], v[186:189], v[40:43]
	v_mfma_f32_16x16x32_bf16 v[40:43], v[140:143], v[190:193], v[40:43]
	v_mfma_f32_16x16x32_bf16 v[48:51], v[128:131], v[186:189], v[48:51]
	v_mfma_f32_16x16x32_bf16 v[48:51], v[132:135], v[190:193], v[48:51]
	v_mfma_f32_16x16x32_bf16 v[32:35], v[128:131], v[194:197], v[32:35]
	v_mfma_f32_16x16x32_bf16 v[32:35], v[132:135], v[198:201], v[32:35]
	v_mfma_f32_16x16x32_bf16 v[24:27], v[136:139], v[194:197], v[24:27]
	v_mfma_f32_16x16x32_bf16 v[24:27], v[140:143], v[198:201], v[24:27]
	v_mfma_f32_16x16x32_bf16 v[20:23], v[144:147], v[194:197], v[20:23]
	v_mfma_f32_16x16x32_bf16 v[20:23], v[148:151], v[198:201], v[20:23]
	v_mfma_f32_16x16x32_bf16 v[12:15], v[152:155], v[194:197], v[12:15]
	v_mfma_f32_16x16x32_bf16 v[12:15], v[156:159], v[198:201], v[12:15]
	v_mfma_f32_16x16x32_bf16 v[0:3], v[152:155], v[202:205], v[0:3]
	v_mfma_f32_16x16x32_bf16 v[0:3], v[156:159], v[206:209], v[0:3]
	v_mfma_f32_16x16x32_bf16 v[4:7], v[144:147], v[202:205], v[4:7]
	v_mfma_f32_16x16x32_bf16 v[4:7], v[148:151], v[206:209], v[4:7]
	v_mfma_f32_16x16x32_bf16 v[8:11], v[136:139], v[202:205], v[8:11]
	v_mfma_f32_16x16x32_bf16 v[8:11], v[140:143], v[206:209], v[8:11]
	v_mfma_f32_16x16x32_bf16 v[16:19], v[128:131], v[202:205], v[16:19]
	v_mfma_f32_16x16x32_bf16 v[16:19], v[132:135], v[206:209], v[16:19]
	s_barrier
	s_add_i32 s42, 0, 0x18000
	s_add_i32 s43, 0, 0x1c000
	v_add_u32_e32 v140, s42, v220
	v_add_u32_e32 v156, s43, v220
	s_mov_b32 m0, s30
	v_lshl_add_u64 v[226:227], v[224:225], 0, s[4:5]
	global_load_lds_dwordx4 v[226:227], off
	v_lshl_add_u64 v[226:227], v[224:225], 0, s[6:7]
	s_mov_b32 m0, s31
	s_nop 0
	global_load_lds_dwordx4 v[226:227], off
	ds_read_b128 v[128:131], v140
	ds_read_b128 v[132:135], v140 offset:1024
	ds_read_b128 v[136:139], v140 offset:2048
	ds_read_b128 v[140:143], v140 offset:3072
	ds_read_b128 v[144:147], v156
	ds_read_b128 v[148:151], v156 offset:1024
	ds_read_b128 v[152:155], v156 offset:2048
	ds_read_b128 v[156:159], v156 offset:3072
	ds_read_b128 v[160:163], v221 offset:32768
	ds_read_b128 v[164:167], v221 offset:33792
	ds_read_b128 v[186:189], v221 offset:34816
	ds_read_b128 v[190:193], v221 offset:35840
	ds_read_b128 v[194:197], v221 offset:36864
	ds_read_b128 v[198:201], v221 offset:37888
	ds_read_b128 v[202:205], v221 offset:38912
	ds_read_b128 v[206:209], v221 offset:39936
	s_waitcnt vmcnt(8)
	s_waitcnt lgkmcnt(0)
	s_barrier
	s_waitcnt lgkmcnt(0)
	v_mfma_f32_16x16x32_bf16 v[124:127], v[128:131], v[160:163], v[124:127]
	v_mfma_f32_16x16x32_bf16 v[124:127], v[132:135], v[164:167], v[124:127]
	v_mfma_f32_16x16x32_bf16 v[120:123], v[136:139], v[160:163], v[120:123]
	v_mfma_f32_16x16x32_bf16 v[120:123], v[140:143], v[164:167], v[120:123]
	v_mfma_f32_16x16x32_bf16 v[116:119], v[144:147], v[160:163], v[116:119]
	v_mfma_f32_16x16x32_bf16 v[116:119], v[148:151], v[164:167], v[116:119]
	v_mfma_f32_16x16x32_bf16 v[108:111], v[152:155], v[160:163], v[108:111]
	v_mfma_f32_16x16x32_bf16 v[108:111], v[156:159], v[164:167], v[108:111]
	v_mfma_f32_16x16x32_bf16 v[92:95], v[152:155], v[186:189], v[92:95]
	v_mfma_f32_16x16x32_bf16 v[92:95], v[156:159], v[190:193], v[92:95]
	v_mfma_f32_16x16x32_bf16 v[100:103], v[144:147], v[186:189], v[100:103]
	v_mfma_f32_16x16x32_bf16 v[100:103], v[148:151], v[190:193], v[100:103]
	v_mfma_f32_16x16x32_bf16 v[104:107], v[136:139], v[186:189], v[104:107]
	v_mfma_f32_16x16x32_bf16 v[104:107], v[140:143], v[190:193], v[104:107]
	v_mfma_f32_16x16x32_bf16 v[112:115], v[128:131], v[186:189], v[112:115]
	v_mfma_f32_16x16x32_bf16 v[112:115], v[132:135], v[190:193], v[112:115]
	v_mfma_f32_16x16x32_bf16 v[96:99], v[128:131], v[194:197], v[96:99]
	v_mfma_f32_16x16x32_bf16 v[96:99], v[132:135], v[198:201], v[96:99]
	v_mfma_f32_16x16x32_bf16 v[88:91], v[136:139], v[194:197], v[88:91]
	v_mfma_f32_16x16x32_bf16 v[88:91], v[140:143], v[198:201], v[88:91]
	v_mfma_f32_16x16x32_bf16 v[84:87], v[144:147], v[194:197], v[84:87]
	v_mfma_f32_16x16x32_bf16 v[84:87], v[148:151], v[198:201], v[84:87]
	v_mfma_f32_16x16x32_bf16 v[76:79], v[152:155], v[194:197], v[76:79]
	v_mfma_f32_16x16x32_bf16 v[76:79], v[156:159], v[198:201], v[76:79]
	v_mfma_f32_16x16x32_bf16 v[64:67], v[152:155], v[202:205], v[64:67]
	v_mfma_f32_16x16x32_bf16 v[64:67], v[156:159], v[206:209], v[64:67]
	v_mfma_f32_16x16x32_bf16 v[68:71], v[144:147], v[202:205], v[68:71]
	v_mfma_f32_16x16x32_bf16 v[68:71], v[148:151], v[206:209], v[68:71]
	v_mfma_f32_16x16x32_bf16 v[72:75], v[136:139], v[202:205], v[72:75]
	v_mfma_f32_16x16x32_bf16 v[72:75], v[140:143], v[206:209], v[72:75]
	v_mfma_f32_16x16x32_bf16 v[80:83], v[128:131], v[202:205], v[80:83]
	v_mfma_f32_16x16x32_bf16 v[80:83], v[132:135], v[206:209], v[80:83]
	s_barrier
	s_add_i32 s42, s42, s74
	v_lshl_add_u64 v[226:227], v[222:223], 0, s[10:11]
	s_mov_b32 m0, s42
	s_nop 0
	global_load_lds_dwordx4 v[226:227], off
	v_lshl_add_u64 v[226:227], v[222:223], 0, s[12:13]
	s_add_i32 m0, s42, 0x2000
	s_add_i32 s42, s43, s74
	global_load_lds_dwordx4 v[226:227], off
	v_lshl_add_u64 v[226:227], v[222:223], 0, s[14:15]
	s_mov_b32 m0, s42
	v_lshl_add_u64 v[222:223], v[222:223], 0, s[16:17]
	global_load_lds_dwordx4 v[226:227], off
	s_add_i32 m0, s42, 0x2000
	s_nop 0
	global_load_lds_dwordx4 v[222:223], off
	v_lshl_add_u64 v[222:223], v[224:225], 0, s[10:11]
	s_mov_b32 m0, s26
	s_nop 0
	global_load_lds_dwordx4 v[222:223], off
	v_lshl_add_u64 v[222:223], v[224:225], 0, s[12:13]
	s_mov_b32 m0, s27
	s_nop 0
	global_load_lds_dwordx4 v[222:223], off
	ds_read_b128 v[160:163], v221 offset:49152
	ds_read_b128 v[164:167], v221 offset:50176
	ds_read_b128 v[186:189], v221 offset:51200
	ds_read_b128 v[190:193], v221 offset:52224
	ds_read_b128 v[194:197], v221 offset:53248
	ds_read_b128 v[198:201], v221 offset:54272
	ds_read_b128 v[202:205], v221 offset:55296
	ds_read_b128 v[206:209], v221 offset:56320
	s_waitcnt vmcnt(8)
	s_waitcnt lgkmcnt(0)
	s_barrier
	s_waitcnt lgkmcnt(0)
	v_mfma_f32_16x16x32_bf16 v[60:63], v[128:131], v[160:163], v[60:63]
	v_mfma_f32_16x16x32_bf16 v[60:63], v[132:135], v[164:167], v[60:63]
	v_mfma_f32_16x16x32_bf16 v[56:59], v[136:139], v[160:163], v[56:59]
	v_mfma_f32_16x16x32_bf16 v[56:59], v[140:143], v[164:167], v[56:59]
	v_mfma_f32_16x16x32_bf16 v[52:55], v[144:147], v[160:163], v[52:55]
	v_mfma_f32_16x16x32_bf16 v[52:55], v[148:151], v[164:167], v[52:55]
	v_mfma_f32_16x16x32_bf16 v[44:47], v[152:155], v[160:163], v[44:47]
	v_mfma_f32_16x16x32_bf16 v[44:47], v[156:159], v[164:167], v[44:47]
	v_mfma_f32_16x16x32_bf16 v[28:31], v[152:155], v[186:189], v[28:31]
	v_mfma_f32_16x16x32_bf16 v[28:31], v[156:159], v[190:193], v[28:31]
	v_mfma_f32_16x16x32_bf16 v[36:39], v[144:147], v[186:189], v[36:39]
	v_mfma_f32_16x16x32_bf16 v[36:39], v[148:151], v[190:193], v[36:39]
	v_mfma_f32_16x16x32_bf16 v[40:43], v[136:139], v[186:189], v[40:43]
	v_mfma_f32_16x16x32_bf16 v[40:43], v[140:143], v[190:193], v[40:43]
	v_mfma_f32_16x16x32_bf16 v[48:51], v[128:131], v[186:189], v[48:51]
	v_mfma_f32_16x16x32_bf16 v[48:51], v[132:135], v[190:193], v[48:51]
	v_mfma_f32_16x16x32_bf16 v[32:35], v[128:131], v[194:197], v[32:35]
	v_mfma_f32_16x16x32_bf16 v[32:35], v[132:135], v[198:201], v[32:35]
	v_mfma_f32_16x16x32_bf16 v[24:27], v[136:139], v[194:197], v[24:27]
	v_mfma_f32_16x16x32_bf16 v[24:27], v[140:143], v[198:201], v[24:27]
	v_mfma_f32_16x16x32_bf16 v[20:23], v[144:147], v[194:197], v[20:23]
	v_mfma_f32_16x16x32_bf16 v[20:23], v[148:151], v[198:201], v[20:23]
	v_mfma_f32_16x16x32_bf16 v[12:15], v[152:155], v[194:197], v[12:15]
	v_mfma_f32_16x16x32_bf16 v[12:15], v[156:159], v[198:201], v[12:15]
	v_mfma_f32_16x16x32_bf16 v[0:3], v[152:155], v[202:205], v[0:3]
	v_mfma_f32_16x16x32_bf16 v[0:3], v[156:159], v[206:209], v[0:3]
	v_mfma_f32_16x16x32_bf16 v[4:7], v[144:147], v[202:205], v[4:7]
	v_mfma_f32_16x16x32_bf16 v[4:7], v[148:151], v[206:209], v[4:7]
	v_mfma_f32_16x16x32_bf16 v[8:11], v[136:139], v[202:205], v[8:11]
	v_mfma_f32_16x16x32_bf16 v[8:11], v[140:143], v[206:209], v[8:11]
	v_mfma_f32_16x16x32_bf16 v[16:19], v[128:131], v[202:205], v[16:19]
	v_mfma_f32_16x16x32_bf16 v[16:19], v[132:135], v[206:209], v[16:19]
	s_barrier
	s_cmp_gt_u32 s70, 13
	s_cbranch_scc0 .LBB0_386
	s_and_b64 vcc, exec, s[58:59]
	s_cbranch_vccz .LBB0_389
	s_barrier

.LBB0_760:
	s_add_i32 s78, s78, 2
	s_mov_b32 s50, s78
	s_ashr_i32 s51, s50, 31
	s_lshl_b64 s[80:81], s[50:51], 7
	s_add_u32 s51, s80, 0x100
	s_addc_u32 s79, s81, 0
	s_add_u32 s82, s48, s51
	s_addc_u32 s83, s49, s79
	s_add_u32 s84, s8, s51
	s_addc_u32 s79, s9, s79
	s_add_i32 s85, 0, 0x10000
	s_cmp_eq_u32 s50, 14
	s_cselect_b32 s51, s35, s83
	s_cselect_b32 s50, s76, s82
	s_cselect_b32 s83, s31, s79
	s_cselect_b32 s82, s77, s84
	s_add_i32 s79, 0, 0x14000
	s_add_u32 s80, s48, s80
	s_addc_u32 s81, s49, s81
	v_lshl_add_u64 v[134:135], s[80:81], 0, v[128:129]
	v_lshl_add_u64 v[224:225], v[134:135], 0, s[14:15]
	s_add_i32 m0, s62, 0xc000
	s_nop 0
	global_load_lds_dwordx4 v[224:225], off
	v_lshl_add_u64 v[134:135], v[134:135], 0, s[16:17]
	s_add_i32 m0, s62, 0xe000
	s_nop 0
	global_load_lds_dwordx4 v[134:135], off
	v_add_u32_e32 v134, s85, v137
	ds_read_b128 v[130:133], v134
	ds_read_b128 v[140:143], v134 offset:1024
	ds_read_b128 v[144:147], v134 offset:2048
	ds_read_b128 v[148:151], v134 offset:3072
	v_add_u32_e32 v134, s79, v137
	ds_read_b128 v[152:155], v134
	ds_read_b128 v[156:159], v134 offset:1024
	ds_read_b128 v[160:163], v134 offset:2048
	ds_read_b128 v[164:167], v134 offset:3072
	ds_read_b128 v[182:185], v138
	ds_read_b128 v[186:189], v138 offset:1024
	ds_read_b128 v[190:193], v138 offset:2048
	ds_read_b128 v[194:197], v138 offset:3072
	ds_read_b128 v[198:201], v138 offset:4096
	ds_read_b128 v[202:205], v138 offset:5120
	ds_read_b128 v[206:209], v138 offset:6144
	ds_read_b128 v[220:223], v138 offset:7168
	s_nop 0
	s_waitcnt vmcnt(8)
	s_waitcnt lgkmcnt(0)
	s_barrier
	s_waitcnt lgkmcnt(0)
	v_mfma_f32_16x16x32_bf16 v[124:127], v[130:133], v[182:185], v[124:127]
	v_mfma_f32_16x16x32_bf16 v[124:127], v[140:143], v[186:189], v[124:127]
	v_mfma_f32_16x16x32_bf16 v[120:123], v[144:147], v[182:185], v[120:123]
	v_mfma_f32_16x16x32_bf16 v[120:123], v[148:151], v[186:189], v[120:123]
	v_mfma_f32_16x16x32_bf16 v[116:119], v[152:155], v[182:185], v[116:119]
	v_mfma_f32_16x16x32_bf16 v[116:119], v[156:159], v[186:189], v[116:119]
	v_mfma_f32_16x16x32_bf16 v[112:115], v[160:163], v[182:185], v[112:115]
	v_mfma_f32_16x16x32_bf16 v[112:115], v[164:167], v[186:189], v[112:115]
	v_mfma_f32_16x16x32_bf16 v[96:99], v[160:163], v[190:193], v[96:99]
	v_mfma_f32_16x16x32_bf16 v[96:99], v[164:167], v[194:197], v[96:99]
	v_mfma_f32_16x16x32_bf16 v[100:103], v[152:155], v[190:193], v[100:103]
	v_mfma_f32_16x16x32_bf16 v[100:103], v[156:159], v[194:197], v[100:103]
	v_mfma_f32_16x16x32_bf16 v[104:107], v[144:147], v[190:193], v[104:107]
	v_mfma_f32_16x16x32_bf16 v[104:107], v[148:151], v[194:197], v[104:107]
	v_mfma_f32_16x16x32_bf16 v[108:111], v[130:133], v[190:193], v[108:111]
	v_mfma_f32_16x16x32_bf16 v[108:111], v[140:143], v[194:197], v[108:111]
	v_mfma_f32_16x16x32_bf16 v[92:95], v[130:133], v[198:201], v[92:95]
	v_mfma_f32_16x16x32_bf16 v[92:95], v[140:143], v[202:205], v[92:95]
	v_mfma_f32_16x16x32_bf16 v[88:91], v[144:147], v[198:201], v[88:91]
	v_mfma_f32_16x16x32_bf16 v[88:91], v[148:151], v[202:205], v[88:91]
	v_mfma_f32_16x16x32_bf16 v[84:87], v[152:155], v[198:201], v[84:87]
	v_mfma_f32_16x16x32_bf16 v[84:87], v[156:159], v[202:205], v[84:87]
	v_mfma_f32_16x16x32_bf16 v[80:83], v[160:163], v[198:201], v[80:83]
	v_mfma_f32_16x16x32_bf16 v[80:83], v[164:167], v[202:205], v[80:83]
	v_mfma_f32_16x16x32_bf16 v[64:67], v[160:163], v[206:209], v[64:67]
	v_mfma_f32_16x16x32_bf16 v[64:67], v[164:167], v[220:223], v[64:67]
	v_mfma_f32_16x16x32_bf16 v[68:71], v[152:155], v[206:209], v[68:71]
	v_mfma_f32_16x16x32_bf16 v[68:71], v[156:159], v[220:223], v[68:71]
	v_mfma_f32_16x16x32_bf16 v[72:75], v[144:147], v[206:209], v[72:75]
	v_mfma_f32_16x16x32_bf16 v[72:75], v[148:151], v[220:223], v[72:75]
	v_mfma_f32_16x16x32_bf16 v[76:79], v[130:133], v[206:209], v[76:79]
	v_mfma_f32_16x16x32_bf16 v[76:79], v[140:143], v[220:223], v[76:79]
	s_barrier
	s_add_i32 s80, s85, s59
	v_lshl_add_u64 v[134:135], s[82:83], 0, v[172:173]
	s_mov_b32 m0, s80
	s_nop 0
	global_load_lds_dwordx4 v[134:135], off
	v_lshl_add_u64 v[224:225], v[134:135], 0, s[40:41]
	s_add_i32 m0, s80, 0x2000
	s_add_i32 s79, s79, s59
	global_load_lds_dwordx4 v[224:225], off
	v_lshl_add_u64 v[224:225], v[134:135], 0, s[4:5]
	s_mov_b32 m0, s79
	s_nop 0
	global_load_lds_dwordx4 v[224:225], off
	v_lshl_add_u64 v[224:225], v[134:135], 0, s[6:7]
	s_add_i32 m0, s79, 0x2000
	s_nop 0
	global_load_lds_dwordx4 v[224:225], off
	v_lshl_add_u64 v[224:225], s[50:51], 0, v[128:129]
	s_mov_b32 m0, s62
	v_lshl_add_u64 v[226:227], v[224:225], 0, s[40:41]
	global_load_lds_dwordx4 v[224:225], off
	s_mov_b32 m0, s63
	s_nop 0
	global_load_lds_dwordx4 v[226:227], off
	ds_read_b128 v[182:185], v138 offset:16384
	ds_read_b128 v[186:189], v138 offset:17408
	ds_read_b128 v[190:193], v138 offset:18432
	ds_read_b128 v[194:197], v138 offset:19456
	ds_read_b128 v[198:201], v138 offset:20480
	ds_read_b128 v[202:205], v138 offset:21504
	ds_read_b128 v[206:209], v138 offset:22528
	ds_read_b128 v[220:223], v138 offset:23552
	s_waitcnt vmcnt(8)
	s_waitcnt lgkmcnt(0)
	s_barrier
	s_waitcnt lgkmcnt(0)
	v_mfma_f32_16x16x32_bf16 v[60:63], v[130:133], v[182:185], v[60:63]
	v_mfma_f32_16x16x32_bf16 v[60:63], v[140:143], v[186:189], v[60:63]
	v_mfma_f32_16x16x32_bf16 v[56:59], v[144:147], v[182:185], v[56:59]
	v_mfma_f32_16x16x32_bf16 v[56:59], v[148:151], v[186:189], v[56:59]
	v_mfma_f32_16x16x32_bf16 v[52:55], v[152:155], v[182:185], v[52:55]
	v_mfma_f32_16x16x32_bf16 v[52:55], v[156:159], v[186:189], v[52:55]
	v_mfma_f32_16x16x32_bf16 v[48:51], v[160:163], v[182:185], v[48:51]
	v_mfma_f32_16x16x32_bf16 v[48:51], v[164:167], v[186:189], v[48:51]
	v_mfma_f32_16x16x32_bf16 v[32:35], v[160:163], v[190:193], v[32:35]
	v_mfma_f32_16x16x32_bf16 v[32:35], v[164:167], v[194:197], v[32:35]
	v_mfma_f32_16x16x32_bf16 v[36:39], v[152:155], v[190:193], v[36:39]
	v_mfma_f32_16x16x32_bf16 v[36:39], v[156:159], v[194:197], v[36:39]
	v_mfma_f32_16x16x32_bf16 v[40:43], v[144:147], v[190:193], v[40:43]
	v_mfma_f32_16x16x32_bf16 v[40:43], v[148:151], v[194:197], v[40:43]
	v_mfma_f32_16x16x32_bf16 v[44:47], v[130:133], v[190:193], v[44:47]
	v_mfma_f32_16x16x32_bf16 v[44:47], v[140:143], v[194:197], v[44:47]
	v_mfma_f32_16x16x32_bf16 v[28:31], v[130:133], v[198:201], v[28:31]
	v_mfma_f32_16x16x32_bf16 v[28:31], v[140:143], v[202:205], v[28:31]
	v_mfma_f32_16x16x32_bf16 v[24:27], v[144:147], v[198:201], v[24:27]
	v_mfma_f32_16x16x32_bf16 v[24:27], v[148:151], v[202:205], v[24:27]
	v_mfma_f32_16x16x32_bf16 v[20:23], v[152:155], v[198:201], v[20:23]
	v_mfma_f32_16x16x32_bf16 v[20:23], v[156:159], v[202:205], v[20:23]
	v_mfma_f32_16x16x32_bf16 v[16:19], v[160:163], v[198:201], v[16:19]
	v_mfma_f32_16x16x32_bf16 v[16:19], v[164:167], v[202:205], v[16:19]
	v_mfma_f32_16x16x32_bf16 v[0:3], v[160:163], v[206:209], v[0:3]
	v_mfma_f32_16x16x32_bf16 v[0:3], v[164:167], v[220:223], v[0:3]
	v_mfma_f32_16x16x32_bf16 v[4:7], v[152:155], v[206:209], v[4:7]
	v_mfma_f32_16x16x32_bf16 v[4:7], v[156:159], v[220:223], v[4:7]
	v_mfma_f32_16x16x32_bf16 v[8:11], v[144:147], v[206:209], v[8:11]
	v_mfma_f32_16x16x32_bf16 v[8:11], v[148:151], v[220:223], v[8:11]
	v_mfma_f32_16x16x32_bf16 v[12:15], v[130:133], v[206:209], v[12:15]
	v_mfma_f32_16x16x32_bf16 v[12:15], v[140:143], v[220:223], v[12:15]
	s_barrier
	s_mov_b32 m0, s68
	v_lshl_add_u64 v[226:227], v[224:225], 0, s[4:5]
	global_load_lds_dwordx4 v[226:227], off
	v_lshl_add_u64 v[226:227], v[224:225], 0, s[6:7]
	s_mov_b32 m0, s69
	s_nop 0
	global_load_lds_dwordx4 v[226:227], off
	s_add_i32 s50, 0, 0x18000
	v_add_u32_e32 v139, s50, v137
	s_add_i32 s51, 0, 0x1c000
	ds_read_b128 v[130:133], v139
	ds_read_b128 v[140:143], v139 offset:1024
	ds_read_b128 v[144:147], v139 offset:2048
	ds_read_b128 v[148:151], v139 offset:3072
	v_add_u32_e32 v139, s51, v137
	ds_read_b128 v[152:155], v139
	ds_read_b128 v[156:159], v139 offset:1024
	ds_read_b128 v[160:163], v139 offset:2048
	ds_read_b128 v[164:167], v139 offset:3072
	ds_read_b128 v[182:185], v138 offset:32768
	ds_read_b128 v[186:189], v138 offset:33792
	ds_read_b128 v[190:193], v138 offset:34816
	ds_read_b128 v[194:197], v138 offset:35840
	ds_read_b128 v[198:201], v138 offset:36864
	ds_read_b128 v[202:205], v138 offset:37888
	ds_read_b128 v[206:209], v138 offset:38912
	ds_read_b128 v[220:223], v138 offset:39936
	s_nop 0
	s_waitcnt vmcnt(8)
	s_waitcnt lgkmcnt(0)
	s_barrier
	s_waitcnt lgkmcnt(0)
	v_mfma_f32_16x16x32_bf16 v[124:127], v[130:133], v[182:185], v[124:127]
	v_mfma_f32_16x16x32_bf16 v[124:127], v[140:143], v[186:189], v[124:127]
	v_mfma_f32_16x16x32_bf16 v[120:123], v[144:147], v[182:185], v[120:123]
	v_mfma_f32_16x16x32_bf16 v[120:123], v[148:151], v[186:189], v[120:123]
	v_mfma_f32_16x16x32_bf16 v[116:119], v[152:155], v[182:185], v[116:119]
	v_mfma_f32_16x16x32_bf16 v[116:119], v[156:159], v[186:189], v[116:119]
	v_mfma_f32_16x16x32_bf16 v[112:115], v[160:163], v[182:185], v[112:115]
	v_mfma_f32_16x16x32_bf16 v[112:115], v[164:167], v[186:189], v[112:115]
	v_mfma_f32_16x16x32_bf16 v[96:99], v[160:163], v[190:193], v[96:99]
	v_mfma_f32_16x16x32_bf16 v[96:99], v[164:167], v[194:197], v[96:99]
	v_mfma_f32_16x16x32_bf16 v[100:103], v[152:155], v[190:193], v[100:103]
	v_mfma_f32_16x16x32_bf16 v[100:103], v[156:159], v[194:197], v[100:103]
	v_mfma_f32_16x16x32_bf16 v[104:107], v[144:147], v[190:193], v[104:107]
	v_mfma_f32_16x16x32_bf16 v[104:107], v[148:151], v[194:197], v[104:107]
	v_mfma_f32_16x16x32_bf16 v[108:111], v[130:133], v[190:193], v[108:111]
	v_mfma_f32_16x16x32_bf16 v[108:111], v[140:143], v[194:197], v[108:111]
	v_mfma_f32_16x16x32_bf16 v[92:95], v[130:133], v[198:201], v[92:95]
	v_mfma_f32_16x16x32_bf16 v[92:95], v[140:143], v[202:205], v[92:95]
	v_mfma_f32_16x16x32_bf16 v[88:91], v[144:147], v[198:201], v[88:91]
	v_mfma_f32_16x16x32_bf16 v[88:91], v[148:151], v[202:205], v[88:91]
	v_mfma_f32_16x16x32_bf16 v[84:87], v[152:155], v[198:201], v[84:87]
	v_mfma_f32_16x16x32_bf16 v[84:87], v[156:159], v[202:205], v[84:87]
	v_mfma_f32_16x16x32_bf16 v[80:83], v[160:163], v[198:201], v[80:83]
	v_mfma_f32_16x16x32_bf16 v[80:83], v[164:167], v[202:205], v[80:83]
	v_mfma_f32_16x16x32_bf16 v[64:67], v[160:163], v[206:209], v[64:67]
	v_mfma_f32_16x16x32_bf16 v[64:67], v[164:167], v[220:223], v[64:67]
	v_mfma_f32_16x16x32_bf16 v[68:71], v[152:155], v[206:209], v[68:71]
	v_mfma_f32_16x16x32_bf16 v[68:71], v[156:159], v[220:223], v[68:71]
	v_mfma_f32_16x16x32_bf16 v[72:75], v[144:147], v[206:209], v[72:75]
	v_mfma_f32_16x16x32_bf16 v[72:75], v[148:151], v[220:223], v[72:75]
	v_mfma_f32_16x16x32_bf16 v[76:79], v[130:133], v[206:209], v[76:79]
	v_mfma_f32_16x16x32_bf16 v[76:79], v[140:143], v[220:223], v[76:79]
	s_barrier
	s_add_i32 s50, s50, s59
	v_lshl_add_u64 v[226:227], v[134:135], 0, s[10:11]
	s_mov_b32 m0, s50
	s_nop 0
	global_load_lds_dwordx4 v[226:227], off
	v_lshl_add_u64 v[226:227], v[134:135], 0, s[12:13]
	s_add_i32 m0, s50, 0x2000
	s_add_i32 s50, s51, s59
	global_load_lds_dwordx4 v[226:227], off
	v_lshl_add_u64 v[226:227], v[134:135], 0, s[14:15]
	s_mov_b32 m0, s50
	v_lshl_add_u64 v[134:135], v[134:135], 0, s[16:17]
	global_load_lds_dwordx4 v[226:227], off
	s_add_i32 m0, s50, 0x2000
	s_nop 0
	global_load_lds_dwordx4 v[134:135], off
	v_lshl_add_u64 v[134:135], v[224:225], 0, s[10:11]
	s_mov_b32 m0, s72
	s_nop 0
	global_load_lds_dwordx4 v[134:135], off
	v_lshl_add_u64 v[134:135], v[224:225], 0, s[12:13]
	s_mov_b32 m0, s73
	s_nop 0
	global_load_lds_dwordx4 v[134:135], off
	ds_read_b128 v[182:185], v138 offset:49152
	ds_read_b128 v[186:189], v138 offset:50176
	ds_read_b128 v[190:193], v138 offset:51200
	ds_read_b128 v[194:197], v138 offset:52224
	ds_read_b128 v[198:201], v138 offset:53248
	ds_read_b128 v[202:205], v138 offset:54272
	ds_read_b128 v[206:209], v138 offset:55296
	ds_read_b128 v[220:223], v138 offset:56320
	s_waitcnt vmcnt(8)
	s_waitcnt lgkmcnt(0)
	s_barrier
	s_waitcnt lgkmcnt(0)
	v_mfma_f32_16x16x32_bf16 v[60:63], v[130:133], v[182:185], v[60:63]
	v_mfma_f32_16x16x32_bf16 v[60:63], v[140:143], v[186:189], v[60:63]
	v_mfma_f32_16x16x32_bf16 v[56:59], v[144:147], v[182:185], v[56:59]
	v_mfma_f32_16x16x32_bf16 v[56:59], v[148:151], v[186:189], v[56:59]
	v_mfma_f32_16x16x32_bf16 v[52:55], v[152:155], v[182:185], v[52:55]
	v_mfma_f32_16x16x32_bf16 v[52:55], v[156:159], v[186:189], v[52:55]
	v_mfma_f32_16x16x32_bf16 v[48:51], v[160:163], v[182:185], v[48:51]
	v_mfma_f32_16x16x32_bf16 v[48:51], v[164:167], v[186:189], v[48:51]
	v_mfma_f32_16x16x32_bf16 v[32:35], v[160:163], v[190:193], v[32:35]
	v_mfma_f32_16x16x32_bf16 v[32:35], v[164:167], v[194:197], v[32:35]
	v_mfma_f32_16x16x32_bf16 v[36:39], v[152:155], v[190:193], v[36:39]
	v_mfma_f32_16x16x32_bf16 v[36:39], v[156:159], v[194:197], v[36:39]
	v_mfma_f32_16x16x32_bf16 v[40:43], v[144:147], v[190:193], v[40:43]
	v_mfma_f32_16x16x32_bf16 v[40:43], v[148:151], v[194:197], v[40:43]
	v_mfma_f32_16x16x32_bf16 v[44:47], v[130:133], v[190:193], v[44:47]
	v_mfma_f32_16x16x32_bf16 v[44:47], v[140:143], v[194:197], v[44:47]
	v_mfma_f32_16x16x32_bf16 v[28:31], v[130:133], v[198:201], v[28:31]
	v_mfma_f32_16x16x32_bf16 v[28:31], v[140:143], v[202:205], v[28:31]
	v_mfma_f32_16x16x32_bf16 v[24:27], v[144:147], v[198:201], v[24:27]
	v_mfma_f32_16x16x32_bf16 v[24:27], v[148:151], v[202:205], v[24:27]
	v_mfma_f32_16x16x32_bf16 v[20:23], v[152:155], v[198:201], v[20:23]
	v_mfma_f32_16x16x32_bf16 v[20:23], v[156:159], v[202:205], v[20:23]
	v_mfma_f32_16x16x32_bf16 v[16:19], v[160:163], v[198:201], v[16:19]
	v_mfma_f32_16x16x32_bf16 v[16:19], v[164:167], v[202:205], v[16:19]
	v_mfma_f32_16x16x32_bf16 v[0:3], v[160:163], v[206:209], v[0:3]
	v_mfma_f32_16x16x32_bf16 v[0:3], v[164:167], v[220:223], v[0:3]
	v_mfma_f32_16x16x32_bf16 v[4:7], v[152:155], v[206:209], v[4:7]
	v_mfma_f32_16x16x32_bf16 v[4:7], v[156:159], v[220:223], v[4:7]
	v_mfma_f32_16x16x32_bf16 v[8:11], v[144:147], v[206:209], v[8:11]
	v_mfma_f32_16x16x32_bf16 v[8:11], v[148:151], v[220:223], v[8:11]
	v_mfma_f32_16x16x32_bf16 v[12:15], v[130:133], v[206:209], v[12:15]
	v_mfma_f32_16x16x32_bf16 v[12:15], v[140:143], v[220:223], v[12:15]
	s_barrier
	s_cmp_gt_u32 s78, 13
	s_cbranch_scc0 .LBB0_760
	s_and_b64 vcc, exec, s[28:29]
	s_cbranch_vccz .LBB0_763
	s_barrier

.LBB0_784:
	s_add_i32 s80, s80, 2
	s_mov_b32 s48, s80
	s_ashr_i32 s49, s48, 31
	s_lshl_b64 s[82:83], s[48:49], 7
	s_add_u32 s49, s82, 0x100
	s_addc_u32 s81, s83, 0
	s_add_u32 s84, s42, s49
	s_addc_u32 s85, s43, s81
	s_add_u32 s86, s8, s49
	s_addc_u32 s81, s9, s81
	s_add_i32 s87, 0, 0x10000
	s_cmp_eq_u32 s48, 14
	s_cselect_b32 s49, s39, s85
	s_cselect_b32 s48, s72, s84
	s_cselect_b32 s85, s35, s81
	s_cselect_b32 s84, s73, s86
	s_add_i32 s81, 0, 0x14000
	s_add_u32 s82, s42, s82
	s_addc_u32 s83, s43, s83
	v_lshl_add_u64 v[134:135], s[82:83], 0, v[128:129]
	v_lshl_add_u64 v[224:225], v[134:135], 0, s[14:15]
	s_add_i32 m0, s74, 0xc000
	s_nop 0
	global_load_lds_dwordx4 v[224:225], off
	v_lshl_add_u64 v[134:135], v[134:135], 0, s[16:17]
	s_add_i32 m0, s74, 0xe000
	s_nop 0
	global_load_lds_dwordx4 v[134:135], off
	v_add_u32_e32 v134, s87, v137
	ds_read_b128 v[130:133], v134
	ds_read_b128 v[140:143], v134 offset:1024
	ds_read_b128 v[144:147], v134 offset:2048
	ds_read_b128 v[148:151], v134 offset:3072
	v_add_u32_e32 v134, s81, v137
	ds_read_b128 v[152:155], v134
	ds_read_b128 v[156:159], v134 offset:1024
	ds_read_b128 v[160:163], v134 offset:2048
	ds_read_b128 v[164:167], v134 offset:3072
	ds_read_b128 v[182:185], v138
	ds_read_b128 v[186:189], v138 offset:1024
	ds_read_b128 v[190:193], v138 offset:2048
	ds_read_b128 v[194:197], v138 offset:3072
	ds_read_b128 v[198:201], v138 offset:4096
	ds_read_b128 v[202:205], v138 offset:5120
	ds_read_b128 v[206:209], v138 offset:6144
	ds_read_b128 v[220:223], v138 offset:7168
	s_nop 0
	s_waitcnt vmcnt(8)
	s_waitcnt lgkmcnt(0)
	s_barrier
	s_waitcnt lgkmcnt(0)
	v_mfma_f32_16x16x32_bf16 v[124:127], v[130:133], v[182:185], v[124:127]
	v_mfma_f32_16x16x32_bf16 v[124:127], v[140:143], v[186:189], v[124:127]
	v_mfma_f32_16x16x32_bf16 v[120:123], v[144:147], v[182:185], v[120:123]
	v_mfma_f32_16x16x32_bf16 v[120:123], v[148:151], v[186:189], v[120:123]
	v_mfma_f32_16x16x32_bf16 v[116:119], v[152:155], v[182:185], v[116:119]
	v_mfma_f32_16x16x32_bf16 v[116:119], v[156:159], v[186:189], v[116:119]
	v_mfma_f32_16x16x32_bf16 v[112:115], v[160:163], v[182:185], v[112:115]
	v_mfma_f32_16x16x32_bf16 v[112:115], v[164:167], v[186:189], v[112:115]
	v_mfma_f32_16x16x32_bf16 v[96:99], v[160:163], v[190:193], v[96:99]
	v_mfma_f32_16x16x32_bf16 v[96:99], v[164:167], v[194:197], v[96:99]
	v_mfma_f32_16x16x32_bf16 v[100:103], v[152:155], v[190:193], v[100:103]
	v_mfma_f32_16x16x32_bf16 v[100:103], v[156:159], v[194:197], v[100:103]
	v_mfma_f32_16x16x32_bf16 v[104:107], v[144:147], v[190:193], v[104:107]
	v_mfma_f32_16x16x32_bf16 v[104:107], v[148:151], v[194:197], v[104:107]
	v_mfma_f32_16x16x32_bf16 v[108:111], v[130:133], v[190:193], v[108:111]
	v_mfma_f32_16x16x32_bf16 v[108:111], v[140:143], v[194:197], v[108:111]
	v_mfma_f32_16x16x32_bf16 v[92:95], v[130:133], v[198:201], v[92:95]
	v_mfma_f32_16x16x32_bf16 v[92:95], v[140:143], v[202:205], v[92:95]
	v_mfma_f32_16x16x32_bf16 v[88:91], v[144:147], v[198:201], v[88:91]
	v_mfma_f32_16x16x32_bf16 v[88:91], v[148:151], v[202:205], v[88:91]
	v_mfma_f32_16x16x32_bf16 v[84:87], v[152:155], v[198:201], v[84:87]
	v_mfma_f32_16x16x32_bf16 v[84:87], v[156:159], v[202:205], v[84:87]
	v_mfma_f32_16x16x32_bf16 v[80:83], v[160:163], v[198:201], v[80:83]
	v_mfma_f32_16x16x32_bf16 v[80:83], v[164:167], v[202:205], v[80:83]
	v_mfma_f32_16x16x32_bf16 v[64:67], v[160:163], v[206:209], v[64:67]
	v_mfma_f32_16x16x32_bf16 v[64:67], v[164:167], v[220:223], v[64:67]
	v_mfma_f32_16x16x32_bf16 v[68:71], v[152:155], v[206:209], v[68:71]
	v_mfma_f32_16x16x32_bf16 v[68:71], v[156:159], v[220:223], v[68:71]
	v_mfma_f32_16x16x32_bf16 v[72:75], v[144:147], v[206:209], v[72:75]
	v_mfma_f32_16x16x32_bf16 v[72:75], v[148:151], v[220:223], v[72:75]
	v_mfma_f32_16x16x32_bf16 v[76:79], v[130:133], v[206:209], v[76:79]
	v_mfma_f32_16x16x32_bf16 v[76:79], v[140:143], v[220:223], v[76:79]
	s_barrier
	s_add_i32 s82, s87, s63
	v_lshl_add_u64 v[134:135], s[84:85], 0, v[172:173]
	s_mov_b32 m0, s82
	s_nop 0
	global_load_lds_dwordx4 v[134:135], off
	v_lshl_add_u64 v[224:225], v[134:135], 0, s[40:41]
	s_add_i32 m0, s82, 0x2000
	s_add_i32 s81, s81, s63
	global_load_lds_dwordx4 v[224:225], off
	v_lshl_add_u64 v[224:225], v[134:135], 0, s[4:5]
	s_mov_b32 m0, s81
	s_nop 0
	global_load_lds_dwordx4 v[224:225], off
	v_lshl_add_u64 v[224:225], v[134:135], 0, s[6:7]
	s_add_i32 m0, s81, 0x2000
	s_nop 0
	global_load_lds_dwordx4 v[224:225], off
	v_lshl_add_u64 v[224:225], s[48:49], 0, v[128:129]
	s_mov_b32 m0, s74
	v_lshl_add_u64 v[226:227], v[224:225], 0, s[40:41]
	global_load_lds_dwordx4 v[224:225], off
	s_mov_b32 m0, s75
	s_nop 0
	global_load_lds_dwordx4 v[226:227], off
	ds_read_b128 v[182:185], v138 offset:16384
	ds_read_b128 v[186:189], v138 offset:17408
	ds_read_b128 v[190:193], v138 offset:18432
	ds_read_b128 v[194:197], v138 offset:19456
	ds_read_b128 v[198:201], v138 offset:20480
	ds_read_b128 v[202:205], v138 offset:21504
	ds_read_b128 v[206:209], v138 offset:22528
	ds_read_b128 v[220:223], v138 offset:23552
	s_waitcnt vmcnt(8)
	s_waitcnt lgkmcnt(0)
	s_barrier
	s_waitcnt lgkmcnt(0)
	v_mfma_f32_16x16x32_bf16 v[60:63], v[130:133], v[182:185], v[60:63]
	v_mfma_f32_16x16x32_bf16 v[60:63], v[140:143], v[186:189], v[60:63]
	v_mfma_f32_16x16x32_bf16 v[56:59], v[144:147], v[182:185], v[56:59]
	v_mfma_f32_16x16x32_bf16 v[56:59], v[148:151], v[186:189], v[56:59]
	v_mfma_f32_16x16x32_bf16 v[52:55], v[152:155], v[182:185], v[52:55]
	v_mfma_f32_16x16x32_bf16 v[52:55], v[156:159], v[186:189], v[52:55]
	v_mfma_f32_16x16x32_bf16 v[48:51], v[160:163], v[182:185], v[48:51]
	v_mfma_f32_16x16x32_bf16 v[48:51], v[164:167], v[186:189], v[48:51]
	v_mfma_f32_16x16x32_bf16 v[32:35], v[160:163], v[190:193], v[32:35]
	v_mfma_f32_16x16x32_bf16 v[32:35], v[164:167], v[194:197], v[32:35]
	v_mfma_f32_16x16x32_bf16 v[36:39], v[152:155], v[190:193], v[36:39]
	v_mfma_f32_16x16x32_bf16 v[36:39], v[156:159], v[194:197], v[36:39]
	v_mfma_f32_16x16x32_bf16 v[40:43], v[144:147], v[190:193], v[40:43]
	v_mfma_f32_16x16x32_bf16 v[40:43], v[148:151], v[194:197], v[40:43]
	v_mfma_f32_16x16x32_bf16 v[44:47], v[130:133], v[190:193], v[44:47]
	v_mfma_f32_16x16x32_bf16 v[44:47], v[140:143], v[194:197], v[44:47]
	v_mfma_f32_16x16x32_bf16 v[28:31], v[130:133], v[198:201], v[28:31]
	v_mfma_f32_16x16x32_bf16 v[28:31], v[140:143], v[202:205], v[28:31]
	v_mfma_f32_16x16x32_bf16 v[24:27], v[144:147], v[198:201], v[24:27]
	v_mfma_f32_16x16x32_bf16 v[24:27], v[148:151], v[202:205], v[24:27]
	v_mfma_f32_16x16x32_bf16 v[20:23], v[152:155], v[198:201], v[20:23]
	v_mfma_f32_16x16x32_bf16 v[20:23], v[156:159], v[202:205], v[20:23]
	v_mfma_f32_16x16x32_bf16 v[16:19], v[160:163], v[198:201], v[16:19]
	v_mfma_f32_16x16x32_bf16 v[16:19], v[164:167], v[202:205], v[16:19]
	v_mfma_f32_16x16x32_bf16 v[0:3], v[160:163], v[206:209], v[0:3]
	v_mfma_f32_16x16x32_bf16 v[0:3], v[164:167], v[220:223], v[0:3]
	v_mfma_f32_16x16x32_bf16 v[4:7], v[152:155], v[206:209], v[4:7]
	v_mfma_f32_16x16x32_bf16 v[4:7], v[156:159], v[220:223], v[4:7]
	v_mfma_f32_16x16x32_bf16 v[8:11], v[144:147], v[206:209], v[8:11]
	v_mfma_f32_16x16x32_bf16 v[8:11], v[148:151], v[220:223], v[8:11]
	v_mfma_f32_16x16x32_bf16 v[12:15], v[130:133], v[206:209], v[12:15]
	v_mfma_f32_16x16x32_bf16 v[12:15], v[140:143], v[220:223], v[12:15]
	s_barrier
	s_mov_b32 m0, s76
	v_lshl_add_u64 v[226:227], v[224:225], 0, s[4:5]
	global_load_lds_dwordx4 v[226:227], off
	v_lshl_add_u64 v[226:227], v[224:225], 0, s[6:7]
	s_mov_b32 m0, s77
	s_nop 0
	global_load_lds_dwordx4 v[226:227], off
	s_add_i32 s48, 0, 0x18000
	v_add_u32_e32 v139, s48, v137
	s_add_i32 s49, 0, 0x1c000
	ds_read_b128 v[130:133], v139
	ds_read_b128 v[140:143], v139 offset:1024
	ds_read_b128 v[144:147], v139 offset:2048
	ds_read_b128 v[148:151], v139 offset:3072
	v_add_u32_e32 v139, s49, v137
	ds_read_b128 v[152:155], v139
	ds_read_b128 v[156:159], v139 offset:1024
	ds_read_b128 v[160:163], v139 offset:2048
	ds_read_b128 v[164:167], v139 offset:3072
	ds_read_b128 v[182:185], v138 offset:32768
	ds_read_b128 v[186:189], v138 offset:33792
	ds_read_b128 v[190:193], v138 offset:34816
	ds_read_b128 v[194:197], v138 offset:35840
	ds_read_b128 v[198:201], v138 offset:36864
	ds_read_b128 v[202:205], v138 offset:37888
	ds_read_b128 v[206:209], v138 offset:38912
	ds_read_b128 v[220:223], v138 offset:39936
	s_nop 0
	s_waitcnt vmcnt(8)
	s_waitcnt lgkmcnt(0)
	s_barrier
	s_waitcnt lgkmcnt(0)
	v_mfma_f32_16x16x32_bf16 v[124:127], v[130:133], v[182:185], v[124:127]
	v_mfma_f32_16x16x32_bf16 v[124:127], v[140:143], v[186:189], v[124:127]
	v_mfma_f32_16x16x32_bf16 v[120:123], v[144:147], v[182:185], v[120:123]
	v_mfma_f32_16x16x32_bf16 v[120:123], v[148:151], v[186:189], v[120:123]
	v_mfma_f32_16x16x32_bf16 v[116:119], v[152:155], v[182:185], v[116:119]
	v_mfma_f32_16x16x32_bf16 v[116:119], v[156:159], v[186:189], v[116:119]
	v_mfma_f32_16x16x32_bf16 v[112:115], v[160:163], v[182:185], v[112:115]
	v_mfma_f32_16x16x32_bf16 v[112:115], v[164:167], v[186:189], v[112:115]
	v_mfma_f32_16x16x32_bf16 v[96:99], v[160:163], v[190:193], v[96:99]
	v_mfma_f32_16x16x32_bf16 v[96:99], v[164:167], v[194:197], v[96:99]
	v_mfma_f32_16x16x32_bf16 v[100:103], v[152:155], v[190:193], v[100:103]
	v_mfma_f32_16x16x32_bf16 v[100:103], v[156:159], v[194:197], v[100:103]
	v_mfma_f32_16x16x32_bf16 v[104:107], v[144:147], v[190:193], v[104:107]
	v_mfma_f32_16x16x32_bf16 v[104:107], v[148:151], v[194:197], v[104:107]
	v_mfma_f32_16x16x32_bf16 v[108:111], v[130:133], v[190:193], v[108:111]
	v_mfma_f32_16x16x32_bf16 v[108:111], v[140:143], v[194:197], v[108:111]
	v_mfma_f32_16x16x32_bf16 v[92:95], v[130:133], v[198:201], v[92:95]
	v_mfma_f32_16x16x32_bf16 v[92:95], v[140:143], v[202:205], v[92:95]
	v_mfma_f32_16x16x32_bf16 v[88:91], v[144:147], v[198:201], v[88:91]
	v_mfma_f32_16x16x32_bf16 v[88:91], v[148:151], v[202:205], v[88:91]
	v_mfma_f32_16x16x32_bf16 v[84:87], v[152:155], v[198:201], v[84:87]
	v_mfma_f32_16x16x32_bf16 v[84:87], v[156:159], v[202:205], v[84:87]
	v_mfma_f32_16x16x32_bf16 v[80:83], v[160:163], v[198:201], v[80:83]
	v_mfma_f32_16x16x32_bf16 v[80:83], v[164:167], v[202:205], v[80:83]
	v_mfma_f32_16x16x32_bf16 v[64:67], v[160:163], v[206:209], v[64:67]
	v_mfma_f32_16x16x32_bf16 v[64:67], v[164:167], v[220:223], v[64:67]
	v_mfma_f32_16x16x32_bf16 v[68:71], v[152:155], v[206:209], v[68:71]
	v_mfma_f32_16x16x32_bf16 v[68:71], v[156:159], v[220:223], v[68:71]
	v_mfma_f32_16x16x32_bf16 v[72:75], v[144:147], v[206:209], v[72:75]
	v_mfma_f32_16x16x32_bf16 v[72:75], v[148:151], v[220:223], v[72:75]
	v_mfma_f32_16x16x32_bf16 v[76:79], v[130:133], v[206:209], v[76:79]
	v_mfma_f32_16x16x32_bf16 v[76:79], v[140:143], v[220:223], v[76:79]
	s_barrier
	s_add_i32 s48, s48, s63
	v_lshl_add_u64 v[226:227], v[134:135], 0, s[10:11]
	s_mov_b32 m0, s48
	s_nop 0
	global_load_lds_dwordx4 v[226:227], off
	v_lshl_add_u64 v[226:227], v[134:135], 0, s[12:13]
	s_add_i32 m0, s48, 0x2000
	s_add_i32 s48, s49, s63
	global_load_lds_dwordx4 v[226:227], off
	v_lshl_add_u64 v[226:227], v[134:135], 0, s[14:15]
	s_mov_b32 m0, s48
	v_lshl_add_u64 v[134:135], v[134:135], 0, s[16:17]
	global_load_lds_dwordx4 v[226:227], off
	s_add_i32 m0, s48, 0x2000
	s_nop 0
	global_load_lds_dwordx4 v[134:135], off
	v_lshl_add_u64 v[134:135], v[224:225], 0, s[10:11]
	s_mov_b32 m0, s68
	s_nop 0
	global_load_lds_dwordx4 v[134:135], off
	v_lshl_add_u64 v[134:135], v[224:225], 0, s[12:13]
	s_mov_b32 m0, s69
	s_nop 0
	global_load_lds_dwordx4 v[134:135], off
	ds_read_b128 v[182:185], v138 offset:49152
	ds_read_b128 v[186:189], v138 offset:50176
	ds_read_b128 v[190:193], v138 offset:51200
	ds_read_b128 v[194:197], v138 offset:52224
	ds_read_b128 v[198:201], v138 offset:53248
	ds_read_b128 v[202:205], v138 offset:54272
	ds_read_b128 v[206:209], v138 offset:55296
	ds_read_b128 v[220:223], v138 offset:56320
	s_waitcnt vmcnt(8)
	s_waitcnt lgkmcnt(0)
	s_barrier
	s_waitcnt lgkmcnt(0)
	v_mfma_f32_16x16x32_bf16 v[60:63], v[130:133], v[182:185], v[60:63]
	v_mfma_f32_16x16x32_bf16 v[60:63], v[140:143], v[186:189], v[60:63]
	v_mfma_f32_16x16x32_bf16 v[56:59], v[144:147], v[182:185], v[56:59]
	v_mfma_f32_16x16x32_bf16 v[56:59], v[148:151], v[186:189], v[56:59]
	v_mfma_f32_16x16x32_bf16 v[52:55], v[152:155], v[182:185], v[52:55]
	v_mfma_f32_16x16x32_bf16 v[52:55], v[156:159], v[186:189], v[52:55]
	v_mfma_f32_16x16x32_bf16 v[48:51], v[160:163], v[182:185], v[48:51]
	v_mfma_f32_16x16x32_bf16 v[48:51], v[164:167], v[186:189], v[48:51]
	v_mfma_f32_16x16x32_bf16 v[32:35], v[160:163], v[190:193], v[32:35]
	v_mfma_f32_16x16x32_bf16 v[32:35], v[164:167], v[194:197], v[32:35]
	v_mfma_f32_16x16x32_bf16 v[36:39], v[152:155], v[190:193], v[36:39]
	v_mfma_f32_16x16x32_bf16 v[36:39], v[156:159], v[194:197], v[36:39]
	v_mfma_f32_16x16x32_bf16 v[40:43], v[144:147], v[190:193], v[40:43]
	v_mfma_f32_16x16x32_bf16 v[40:43], v[148:151], v[194:197], v[40:43]
	v_mfma_f32_16x16x32_bf16 v[44:47], v[130:133], v[190:193], v[44:47]
	v_mfma_f32_16x16x32_bf16 v[44:47], v[140:143], v[194:197], v[44:47]
	v_mfma_f32_16x16x32_bf16 v[28:31], v[130:133], v[198:201], v[28:31]
	v_mfma_f32_16x16x32_bf16 v[28:31], v[140:143], v[202:205], v[28:31]
	v_mfma_f32_16x16x32_bf16 v[24:27], v[144:147], v[198:201], v[24:27]
	v_mfma_f32_16x16x32_bf16 v[24:27], v[148:151], v[202:205], v[24:27]
	v_mfma_f32_16x16x32_bf16 v[20:23], v[152:155], v[198:201], v[20:23]
	v_mfma_f32_16x16x32_bf16 v[20:23], v[156:159], v[202:205], v[20:23]
	v_mfma_f32_16x16x32_bf16 v[16:19], v[160:163], v[198:201], v[16:19]
	v_mfma_f32_16x16x32_bf16 v[16:19], v[164:167], v[202:205], v[16:19]
	v_mfma_f32_16x16x32_bf16 v[0:3], v[160:163], v[206:209], v[0:3]
	v_mfma_f32_16x16x32_bf16 v[0:3], v[164:167], v[220:223], v[0:3]
	v_mfma_f32_16x16x32_bf16 v[4:7], v[152:155], v[206:209], v[4:7]
	v_mfma_f32_16x16x32_bf16 v[4:7], v[156:159], v[220:223], v[4:7]
	v_mfma_f32_16x16x32_bf16 v[8:11], v[144:147], v[206:209], v[8:11]
	v_mfma_f32_16x16x32_bf16 v[8:11], v[148:151], v[220:223], v[8:11]
	v_mfma_f32_16x16x32_bf16 v[12:15], v[130:133], v[206:209], v[12:15]
	v_mfma_f32_16x16x32_bf16 v[12:15], v[140:143], v[220:223], v[12:15]
	s_barrier
	s_cmp_gt_u32 s80, 13
	s_cbranch_scc0 .LBB0_784
	s_and_b64 vcc, exec, s[30:31]
	s_cbranch_vccz .LBB0_787
	s_barrier

.LBB0_856:
	s_add_i32 s78, s78, 2
	s_mov_b32 s50, s78
	s_ashr_i32 s51, s50, 31
	s_lshl_b64 s[80:81], s[50:51], 7
	v_lshl_add_u64 v[224:225], v[130:131], 0, s[80:81]
	v_lshl_add_u64 v[226:227], v[224:225], 0, s[10:11]
	s_add_i32 m0, s62, 0xc000
	s_nop 0
	global_load_lds_dwordx4 v[226:227], off
	v_lshl_add_u64 v[224:225], v[224:225], 0, s[12:13]
	s_add_i32 m0, s62, 0xe000
	s_nop 0
	global_load_lds_dwordx4 v[224:225], off
	s_add_u32 s51, s80, 0x100
	s_addc_u32 s79, s81, 0
	s_add_u32 s82, s30, s51
	s_addc_u32 s83, s31, s79
	s_add_u32 s84, s28, s51
	s_addc_u32 s79, s29, s79
	s_add_i32 s85, 0, 0x10000
	s_cmp_eq_u32 s50, 14
	s_cselect_b32 s51, s39, s83
	s_cselect_b32 s50, s76, s82
	v_add_u32_e32 v135, s85, v133
	s_cselect_b32 s83, s35, s79
	s_cselect_b32 s82, s77, s84
	s_add_i32 s79, 0, 0x14000
	ds_read_b128 v[136:139], v135
	ds_read_b128 v[140:143], v135 offset:1024
	ds_read_b128 v[144:147], v135 offset:2048
	ds_read_b128 v[148:151], v135 offset:3072
	v_add_u32_e32 v135, s79, v133
	ds_read_b128 v[152:155], v135
	ds_read_b128 v[156:159], v135 offset:1024
	ds_read_b128 v[160:163], v135 offset:2048
	ds_read_b128 v[164:167], v135 offset:3072
	ds_read_b128 v[182:185], v134
	ds_read_b128 v[186:189], v134 offset:1024
	ds_read_b128 v[190:193], v134 offset:2048
	ds_read_b128 v[194:197], v134 offset:3072
	ds_read_b128 v[198:201], v134 offset:4096
	ds_read_b128 v[202:205], v134 offset:5120
	ds_read_b128 v[206:209], v134 offset:6144
	ds_read_b128 v[220:223], v134 offset:7168
	s_nop 0
	s_waitcnt vmcnt(8)
	s_waitcnt lgkmcnt(0)
	s_barrier
	s_waitcnt lgkmcnt(0)
	v_mfma_f32_16x16x32_bf16 v[124:127], v[136:139], v[182:185], v[124:127]
	v_mfma_f32_16x16x32_bf16 v[124:127], v[140:143], v[186:189], v[124:127]
	v_mfma_f32_16x16x32_bf16 v[120:123], v[144:147], v[182:185], v[120:123]
	v_mfma_f32_16x16x32_bf16 v[120:123], v[148:151], v[186:189], v[120:123]
	v_mfma_f32_16x16x32_bf16 v[108:111], v[152:155], v[182:185], v[108:111]
	v_mfma_f32_16x16x32_bf16 v[108:111], v[156:159], v[186:189], v[108:111]
	v_mfma_f32_16x16x32_bf16 v[104:107], v[160:163], v[182:185], v[104:107]
	v_mfma_f32_16x16x32_bf16 v[104:107], v[164:167], v[186:189], v[104:107]
	v_mfma_f32_16x16x32_bf16 v[88:91], v[160:163], v[190:193], v[88:91]
	v_mfma_f32_16x16x32_bf16 v[88:91], v[164:167], v[194:197], v[88:91]
	v_mfma_f32_16x16x32_bf16 v[92:95], v[152:155], v[190:193], v[92:95]
	v_mfma_f32_16x16x32_bf16 v[92:95], v[156:159], v[194:197], v[92:95]
	v_mfma_f32_16x16x32_bf16 v[112:115], v[144:147], v[190:193], v[112:115]
	v_mfma_f32_16x16x32_bf16 v[112:115], v[148:151], v[194:197], v[112:115]
	v_mfma_f32_16x16x32_bf16 v[116:119], v[136:139], v[190:193], v[116:119]
	v_mfma_f32_16x16x32_bf16 v[116:119], v[140:143], v[194:197], v[116:119]
	v_mfma_f32_16x16x32_bf16 v[100:103], v[136:139], v[198:201], v[100:103]
	v_mfma_f32_16x16x32_bf16 v[100:103], v[140:143], v[202:205], v[100:103]
	v_mfma_f32_16x16x32_bf16 v[96:99], v[144:147], v[198:201], v[96:99]
	v_mfma_f32_16x16x32_bf16 v[96:99], v[148:151], v[202:205], v[96:99]
	v_mfma_f32_16x16x32_bf16 v[76:79], v[152:155], v[198:201], v[76:79]
	v_mfma_f32_16x16x32_bf16 v[76:79], v[156:159], v[202:205], v[76:79]
	v_mfma_f32_16x16x32_bf16 v[72:75], v[160:163], v[198:201], v[72:75]
	v_mfma_f32_16x16x32_bf16 v[72:75], v[164:167], v[202:205], v[72:75]
	v_mfma_f32_16x16x32_bf16 v[64:67], v[160:163], v[206:209], v[64:67]
	v_mfma_f32_16x16x32_bf16 v[64:67], v[164:167], v[220:223], v[64:67]
	v_mfma_f32_16x16x32_bf16 v[68:71], v[152:155], v[206:209], v[68:71]
	v_mfma_f32_16x16x32_bf16 v[68:71], v[156:159], v[220:223], v[68:71]
	v_mfma_f32_16x16x32_bf16 v[80:83], v[144:147], v[206:209], v[80:83]
	v_mfma_f32_16x16x32_bf16 v[80:83], v[148:151], v[220:223], v[80:83]
	v_mfma_f32_16x16x32_bf16 v[84:87], v[136:139], v[206:209], v[84:87]
	v_mfma_f32_16x16x32_bf16 v[84:87], v[140:143], v[220:223], v[84:87]
	s_barrier
	s_add_i32 s80, s85, s59
	v_lshl_add_u64 v[224:225], s[82:83], 0, v[172:173]
	s_mov_b32 m0, s80
	s_nop 0
	global_load_lds_dwordx4 v[224:225], off
	v_lshl_add_u64 v[226:227], v[224:225], 0, s[40:41]
	s_add_i32 m0, s80, 0x2000
	s_add_i32 s79, s79, s59
	global_load_lds_dwordx4 v[226:227], off
	v_lshl_add_u64 v[226:227], v[224:225], 0, s[4:5]
	s_mov_b32 m0, s79
	s_nop 0
	global_load_lds_dwordx4 v[226:227], off
	v_lshl_add_u64 v[226:227], v[224:225], 0, s[6:7]
	s_add_i32 m0, s79, 0x2000
	s_nop 0
	global_load_lds_dwordx4 v[226:227], off
	v_lshl_add_u64 v[226:227], s[50:51], 0, v[128:129]
	s_mov_b32 m0, s62
	v_lshl_add_u64 v[228:229], v[226:227], 0, s[40:41]
	global_load_lds_dwordx4 v[226:227], off
	s_mov_b32 m0, s63
	s_nop 0
	global_load_lds_dwordx4 v[228:229], off
	ds_read_b128 v[182:185], v134 offset:16384
	ds_read_b128 v[186:189], v134 offset:17408
	ds_read_b128 v[190:193], v134 offset:18432
	ds_read_b128 v[194:197], v134 offset:19456
	ds_read_b128 v[198:201], v134 offset:20480
	ds_read_b128 v[202:205], v134 offset:21504
	ds_read_b128 v[206:209], v134 offset:22528
	ds_read_b128 v[220:223], v134 offset:23552
	s_waitcnt vmcnt(8)
	s_waitcnt lgkmcnt(0)
	s_barrier
	s_waitcnt lgkmcnt(0)
	v_mfma_f32_16x16x32_bf16 v[60:63], v[136:139], v[182:185], v[60:63]
	v_mfma_f32_16x16x32_bf16 v[60:63], v[140:143], v[186:189], v[60:63]
	v_mfma_f32_16x16x32_bf16 v[56:59], v[144:147], v[182:185], v[56:59]
	v_mfma_f32_16x16x32_bf16 v[56:59], v[148:151], v[186:189], v[56:59]
	v_mfma_f32_16x16x32_bf16 v[44:47], v[152:155], v[182:185], v[44:47]
	v_mfma_f32_16x16x32_bf16 v[44:47], v[156:159], v[186:189], v[44:47]
	v_mfma_f32_16x16x32_bf16 v[40:43], v[160:163], v[182:185], v[40:43]
	v_mfma_f32_16x16x32_bf16 v[40:43], v[164:167], v[186:189], v[40:43]
	v_mfma_f32_16x16x32_bf16 v[24:27], v[160:163], v[190:193], v[24:27]
	v_mfma_f32_16x16x32_bf16 v[24:27], v[164:167], v[194:197], v[24:27]
	v_mfma_f32_16x16x32_bf16 v[28:31], v[152:155], v[190:193], v[28:31]
	v_mfma_f32_16x16x32_bf16 v[28:31], v[156:159], v[194:197], v[28:31]
	v_mfma_f32_16x16x32_bf16 v[48:51], v[144:147], v[190:193], v[48:51]
	v_mfma_f32_16x16x32_bf16 v[48:51], v[148:151], v[194:197], v[48:51]
	v_mfma_f32_16x16x32_bf16 v[52:55], v[136:139], v[190:193], v[52:55]
	v_mfma_f32_16x16x32_bf16 v[52:55], v[140:143], v[194:197], v[52:55]
	v_mfma_f32_16x16x32_bf16 v[36:39], v[136:139], v[198:201], v[36:39]
	v_mfma_f32_16x16x32_bf16 v[36:39], v[140:143], v[202:205], v[36:39]
	v_mfma_f32_16x16x32_bf16 v[32:35], v[144:147], v[198:201], v[32:35]
	v_mfma_f32_16x16x32_bf16 v[32:35], v[148:151], v[202:205], v[32:35]
	v_mfma_f32_16x16x32_bf16 v[12:15], v[152:155], v[198:201], v[12:15]
	v_mfma_f32_16x16x32_bf16 v[12:15], v[156:159], v[202:205], v[12:15]
	v_mfma_f32_16x16x32_bf16 v[8:11], v[160:163], v[198:201], v[8:11]
	v_mfma_f32_16x16x32_bf16 v[8:11], v[164:167], v[202:205], v[8:11]
	v_mfma_f32_16x16x32_bf16 v[0:3], v[160:163], v[206:209], v[0:3]
	v_mfma_f32_16x16x32_bf16 v[0:3], v[164:167], v[220:223], v[0:3]
	v_mfma_f32_16x16x32_bf16 v[4:7], v[152:155], v[206:209], v[4:7]
	v_mfma_f32_16x16x32_bf16 v[4:7], v[156:159], v[220:223], v[4:7]
	v_mfma_f32_16x16x32_bf16 v[16:19], v[144:147], v[206:209], v[16:19]
	v_mfma_f32_16x16x32_bf16 v[16:19], v[148:151], v[220:223], v[16:19]
	v_mfma_f32_16x16x32_bf16 v[20:23], v[136:139], v[206:209], v[20:23]
	v_mfma_f32_16x16x32_bf16 v[20:23], v[140:143], v[220:223], v[20:23]
	s_barrier
	s_mov_b32 m0, s68
	v_lshl_add_u64 v[228:229], v[226:227], 0, s[4:5]
	global_load_lds_dwordx4 v[228:229], off
	v_lshl_add_u64 v[228:229], v[226:227], 0, s[6:7]
	s_mov_b32 m0, s69
	s_nop 0
	global_load_lds_dwordx4 v[228:229], off
	s_add_i32 s50, 0, 0x18000
	v_add_u32_e32 v135, s50, v133
	s_add_i32 s51, 0, 0x1c000
	ds_read_b128 v[136:139], v135
	ds_read_b128 v[140:143], v135 offset:1024
	ds_read_b128 v[144:147], v135 offset:2048
	ds_read_b128 v[148:151], v135 offset:3072
	v_add_u32_e32 v135, s51, v133
	ds_read_b128 v[152:155], v135
	ds_read_b128 v[156:159], v135 offset:1024
	ds_read_b128 v[160:163], v135 offset:2048
	ds_read_b128 v[164:167], v135 offset:3072
	ds_read_b128 v[182:185], v134 offset:32768
	ds_read_b128 v[186:189], v134 offset:33792
	ds_read_b128 v[190:193], v134 offset:34816
	ds_read_b128 v[194:197], v134 offset:35840
	ds_read_b128 v[198:201], v134 offset:36864
	ds_read_b128 v[202:205], v134 offset:37888
	ds_read_b128 v[206:209], v134 offset:38912
	ds_read_b128 v[220:223], v134 offset:39936
	s_nop 0
	s_waitcnt vmcnt(8)
	s_waitcnt lgkmcnt(0)
	s_barrier
	s_waitcnt lgkmcnt(0)
	v_mfma_f32_16x16x32_bf16 v[124:127], v[136:139], v[182:185], v[124:127]
	v_mfma_f32_16x16x32_bf16 v[124:127], v[140:143], v[186:189], v[124:127]
	v_mfma_f32_16x16x32_bf16 v[120:123], v[144:147], v[182:185], v[120:123]
	v_mfma_f32_16x16x32_bf16 v[120:123], v[148:151], v[186:189], v[120:123]
	v_mfma_f32_16x16x32_bf16 v[108:111], v[152:155], v[182:185], v[108:111]
	v_mfma_f32_16x16x32_bf16 v[108:111], v[156:159], v[186:189], v[108:111]
	v_mfma_f32_16x16x32_bf16 v[104:107], v[160:163], v[182:185], v[104:107]
	v_mfma_f32_16x16x32_bf16 v[104:107], v[164:167], v[186:189], v[104:107]
	v_mfma_f32_16x16x32_bf16 v[88:91], v[160:163], v[190:193], v[88:91]
	v_mfma_f32_16x16x32_bf16 v[88:91], v[164:167], v[194:197], v[88:91]
	v_mfma_f32_16x16x32_bf16 v[92:95], v[152:155], v[190:193], v[92:95]
	v_mfma_f32_16x16x32_bf16 v[92:95], v[156:159], v[194:197], v[92:95]
	v_mfma_f32_16x16x32_bf16 v[112:115], v[144:147], v[190:193], v[112:115]
	v_mfma_f32_16x16x32_bf16 v[112:115], v[148:151], v[194:197], v[112:115]
	v_mfma_f32_16x16x32_bf16 v[116:119], v[136:139], v[190:193], v[116:119]
	v_mfma_f32_16x16x32_bf16 v[116:119], v[140:143], v[194:197], v[116:119]
	v_mfma_f32_16x16x32_bf16 v[100:103], v[136:139], v[198:201], v[100:103]
	v_mfma_f32_16x16x32_bf16 v[100:103], v[140:143], v[202:205], v[100:103]
	v_mfma_f32_16x16x32_bf16 v[96:99], v[144:147], v[198:201], v[96:99]
	v_mfma_f32_16x16x32_bf16 v[96:99], v[148:151], v[202:205], v[96:99]
	v_mfma_f32_16x16x32_bf16 v[76:79], v[152:155], v[198:201], v[76:79]
	v_mfma_f32_16x16x32_bf16 v[76:79], v[156:159], v[202:205], v[76:79]
	v_mfma_f32_16x16x32_bf16 v[72:75], v[160:163], v[198:201], v[72:75]
	v_mfma_f32_16x16x32_bf16 v[72:75], v[164:167], v[202:205], v[72:75]
	v_mfma_f32_16x16x32_bf16 v[64:67], v[160:163], v[206:209], v[64:67]
	v_mfma_f32_16x16x32_bf16 v[64:67], v[164:167], v[220:223], v[64:67]
	v_mfma_f32_16x16x32_bf16 v[68:71], v[152:155], v[206:209], v[68:71]
	v_mfma_f32_16x16x32_bf16 v[68:71], v[156:159], v[220:223], v[68:71]
	v_mfma_f32_16x16x32_bf16 v[80:83], v[144:147], v[206:209], v[80:83]
	v_mfma_f32_16x16x32_bf16 v[80:83], v[148:151], v[220:223], v[80:83]
	v_mfma_f32_16x16x32_bf16 v[84:87], v[136:139], v[206:209], v[84:87]
	v_mfma_f32_16x16x32_bf16 v[84:87], v[140:143], v[220:223], v[84:87]
	s_barrier
	s_add_i32 s50, s50, s59
	v_lshl_add_u64 v[228:229], v[224:225], 0, s[10:11]
	s_mov_b32 m0, s50
	s_nop 0
	global_load_lds_dwordx4 v[228:229], off
	v_lshl_add_u64 v[228:229], v[224:225], 0, s[12:13]
	s_add_i32 m0, s50, 0x2000
	s_add_i32 s50, s51, s59
	global_load_lds_dwordx4 v[228:229], off
	v_lshl_add_u64 v[228:229], v[224:225], 0, s[14:15]
	s_mov_b32 m0, s50
	v_lshl_add_u64 v[224:225], v[224:225], 0, s[16:17]
	global_load_lds_dwordx4 v[228:229], off
	s_add_i32 m0, s50, 0x2000
	s_nop 0
	global_load_lds_dwordx4 v[224:225], off
	v_lshl_add_u64 v[224:225], v[226:227], 0, s[10:11]
	s_mov_b32 m0, s72
	s_nop 0
	global_load_lds_dwordx4 v[224:225], off
	v_lshl_add_u64 v[224:225], v[226:227], 0, s[12:13]
	s_mov_b32 m0, s73
	s_nop 0
	global_load_lds_dwordx4 v[224:225], off
	ds_read_b128 v[182:185], v134 offset:49152
	ds_read_b128 v[186:189], v134 offset:50176
	ds_read_b128 v[190:193], v134 offset:51200
	ds_read_b128 v[194:197], v134 offset:52224
	ds_read_b128 v[198:201], v134 offset:53248
	ds_read_b128 v[202:205], v134 offset:54272
	ds_read_b128 v[206:209], v134 offset:55296
	ds_read_b128 v[220:223], v134 offset:56320
	s_waitcnt vmcnt(8)
	s_waitcnt lgkmcnt(0)
	s_barrier
	s_waitcnt lgkmcnt(0)
	v_mfma_f32_16x16x32_bf16 v[60:63], v[136:139], v[182:185], v[60:63]
	v_mfma_f32_16x16x32_bf16 v[60:63], v[140:143], v[186:189], v[60:63]
	v_mfma_f32_16x16x32_bf16 v[56:59], v[144:147], v[182:185], v[56:59]
	v_mfma_f32_16x16x32_bf16 v[56:59], v[148:151], v[186:189], v[56:59]
	v_mfma_f32_16x16x32_bf16 v[44:47], v[152:155], v[182:185], v[44:47]
	v_mfma_f32_16x16x32_bf16 v[44:47], v[156:159], v[186:189], v[44:47]
	v_mfma_f32_16x16x32_bf16 v[40:43], v[160:163], v[182:185], v[40:43]
	v_mfma_f32_16x16x32_bf16 v[40:43], v[164:167], v[186:189], v[40:43]
	v_mfma_f32_16x16x32_bf16 v[24:27], v[160:163], v[190:193], v[24:27]
	v_mfma_f32_16x16x32_bf16 v[24:27], v[164:167], v[194:197], v[24:27]
	v_mfma_f32_16x16x32_bf16 v[28:31], v[152:155], v[190:193], v[28:31]
	v_mfma_f32_16x16x32_bf16 v[28:31], v[156:159], v[194:197], v[28:31]
	v_mfma_f32_16x16x32_bf16 v[48:51], v[144:147], v[190:193], v[48:51]
	v_mfma_f32_16x16x32_bf16 v[48:51], v[148:151], v[194:197], v[48:51]
	v_mfma_f32_16x16x32_bf16 v[52:55], v[136:139], v[190:193], v[52:55]
	v_mfma_f32_16x16x32_bf16 v[52:55], v[140:143], v[194:197], v[52:55]
	v_mfma_f32_16x16x32_bf16 v[36:39], v[136:139], v[198:201], v[36:39]
	v_mfma_f32_16x16x32_bf16 v[36:39], v[140:143], v[202:205], v[36:39]
	v_mfma_f32_16x16x32_bf16 v[32:35], v[144:147], v[198:201], v[32:35]
	v_mfma_f32_16x16x32_bf16 v[32:35], v[148:151], v[202:205], v[32:35]
	v_mfma_f32_16x16x32_bf16 v[12:15], v[152:155], v[198:201], v[12:15]
	v_mfma_f32_16x16x32_bf16 v[12:15], v[156:159], v[202:205], v[12:15]
	v_mfma_f32_16x16x32_bf16 v[8:11], v[160:163], v[198:201], v[8:11]
	v_mfma_f32_16x16x32_bf16 v[8:11], v[164:167], v[202:205], v[8:11]
	v_mfma_f32_16x16x32_bf16 v[0:3], v[160:163], v[206:209], v[0:3]
	v_mfma_f32_16x16x32_bf16 v[0:3], v[164:167], v[220:223], v[0:3]
	v_mfma_f32_16x16x32_bf16 v[4:7], v[152:155], v[206:209], v[4:7]
	v_mfma_f32_16x16x32_bf16 v[4:7], v[156:159], v[220:223], v[4:7]
	v_mfma_f32_16x16x32_bf16 v[16:19], v[144:147], v[206:209], v[16:19]
	v_mfma_f32_16x16x32_bf16 v[16:19], v[148:151], v[220:223], v[16:19]
	v_mfma_f32_16x16x32_bf16 v[20:23], v[136:139], v[206:209], v[20:23]
	v_mfma_f32_16x16x32_bf16 v[20:23], v[140:143], v[220:223], v[20:23]
	s_barrier
	s_cmp_gt_u32 s78, 13
	s_cbranch_scc0 .LBB0_856
	s_and_b64 vcc, exec, s[8:9]
	s_cbranch_vccz .LBB0_859
	s_barrier

.LBB0_970:
	s_add_i32 s21, s21, 2
	s_mov_b32 s38, s21
	s_ashr_i32 s39, s38, 31
	s_lshl_b64 s[74:75], s[38:39], 7
	s_add_u32 s39, s74, 0x100
	s_addc_u32 s73, s75, 0
	s_add_u32 s76, s34, s39
	s_addc_u32 s77, s35, s73
	s_add_u32 s78, s30, s39
	s_addc_u32 s73, s31, s73
	s_cmp_eq_u32 s38, 14
	s_cselect_b32 s39, s67, s77
	s_cselect_b32 s38, s68, s76
	s_cselect_b32 s77, s23, s73
	s_cselect_b32 s76, s66, s78
	s_add_u32 s74, s34, s74
	s_addc_u32 s75, s35, s75
	v_lshl_add_u64 v[208:209], s[74:75], 0, v[130:131]
	s_mov_b32 m0, s59
	v_lshl_add_u64 v[216:217], v[208:209], 0, s[14:15]
	global_load_lds_dwordx4 v[216:217], off
	v_lshl_add_u64 v[208:209], v[208:209], 0, s[16:17]
	s_mov_b32 m0, s60
	s_nop 0
	global_load_lds_dwordx4 v[208:209], off
	ds_read_b128 v[144:147], v140
	ds_read_b128 v[148:151], v140 offset:1024
	ds_read_b128 v[152:155], v140 offset:2048
	ds_read_b128 v[156:159], v140 offset:3072
	ds_read_b128 v[160:163], v141
	ds_read_b128 v[164:167], v141 offset:1024
	ds_read_b128 v[172:175], v141 offset:2048
	ds_read_b128 v[176:179], v141 offset:3072
	ds_read_b128 v[180:183], v142
	ds_read_b128 v[184:187], v142 offset:1024
	ds_read_b128 v[188:191], v142 offset:2048
	ds_read_b128 v[192:195], v142 offset:3072
	ds_read_b128 v[196:199], v142 offset:4096
	ds_read_b128 v[200:203], v142 offset:5120
	ds_read_b128 v[204:207], v142 offset:6144
	ds_read_b128 v[212:215], v142 offset:7168
	s_waitcnt vmcnt(8)
	s_waitcnt lgkmcnt(0)
	s_barrier
	s_waitcnt lgkmcnt(0)
	v_mfma_f32_16x16x32_bf16 v[124:127], v[144:147], v[180:183], v[124:127]
	v_mfma_f32_16x16x32_bf16 v[124:127], v[148:151], v[184:187], v[124:127]
	v_mfma_f32_16x16x32_bf16 v[112:115], v[152:155], v[180:183], v[112:115]
	v_mfma_f32_16x16x32_bf16 v[112:115], v[156:159], v[184:187], v[112:115]
	v_mfma_f32_16x16x32_bf16 v[120:123], v[160:163], v[180:183], v[120:123]
	v_mfma_f32_16x16x32_bf16 v[120:123], v[164:167], v[184:187], v[120:123]
	v_mfma_f32_16x16x32_bf16 v[116:119], v[172:175], v[180:183], v[116:119]
	v_mfma_f32_16x16x32_bf16 v[116:119], v[176:179], v[184:187], v[116:119]
	v_mfma_f32_16x16x32_bf16 v[100:103], v[172:175], v[188:191], v[100:103]
	v_mfma_f32_16x16x32_bf16 v[100:103], v[176:179], v[192:195], v[100:103]
	v_mfma_f32_16x16x32_bf16 v[104:107], v[160:163], v[188:191], v[104:107]
	v_mfma_f32_16x16x32_bf16 v[104:107], v[164:167], v[192:195], v[104:107]
	v_mfma_f32_16x16x32_bf16 v[96:99], v[152:155], v[188:191], v[96:99]
	v_mfma_f32_16x16x32_bf16 v[96:99], v[156:159], v[192:195], v[96:99]
	v_mfma_f32_16x16x32_bf16 v[108:111], v[144:147], v[188:191], v[108:111]
	v_mfma_f32_16x16x32_bf16 v[108:111], v[148:151], v[192:195], v[108:111]
	v_mfma_f32_16x16x32_bf16 v[92:95], v[144:147], v[196:199], v[92:95]
	v_mfma_f32_16x16x32_bf16 v[92:95], v[148:151], v[200:203], v[92:95]
	v_mfma_f32_16x16x32_bf16 v[80:83], v[152:155], v[196:199], v[80:83]
	v_mfma_f32_16x16x32_bf16 v[80:83], v[156:159], v[200:203], v[80:83]
	v_mfma_f32_16x16x32_bf16 v[88:91], v[160:163], v[196:199], v[88:91]
	v_mfma_f32_16x16x32_bf16 v[88:91], v[164:167], v[200:203], v[88:91]
	v_mfma_f32_16x16x32_bf16 v[84:87], v[172:175], v[196:199], v[84:87]
	v_mfma_f32_16x16x32_bf16 v[84:87], v[176:179], v[200:203], v[84:87]
	v_mfma_f32_16x16x32_bf16 v[68:71], v[172:175], v[204:207], v[68:71]
	v_mfma_f32_16x16x32_bf16 v[68:71], v[176:179], v[212:215], v[68:71]
	v_mfma_f32_16x16x32_bf16 v[72:75], v[160:163], v[204:207], v[72:75]
	v_mfma_f32_16x16x32_bf16 v[72:75], v[164:167], v[212:215], v[72:75]
	v_mfma_f32_16x16x32_bf16 v[64:67], v[152:155], v[204:207], v[64:67]
	v_mfma_f32_16x16x32_bf16 v[64:67], v[156:159], v[212:215], v[64:67]
	v_mfma_f32_16x16x32_bf16 v[76:79], v[144:147], v[204:207], v[76:79]
	v_mfma_f32_16x16x32_bf16 v[76:79], v[148:151], v[212:215], v[76:79]
	s_barrier
	s_mov_b32 m0, s61
	v_lshl_add_u64 v[208:209], s[76:77], 0, v[128:129]
	global_load_lds_dwordx4 v[208:209], off
	v_lshl_add_u64 v[216:217], v[208:209], 0, s[0:1]
	s_mov_b32 m0, s62
	s_nop 0
	global_load_lds_dwordx4 v[216:217], off
	v_lshl_add_u64 v[216:217], v[208:209], 0, s[2:3]
	s_mov_b32 m0, s63
	s_nop 0
	global_load_lds_dwordx4 v[216:217], off
	v_lshl_add_u64 v[216:217], v[208:209], 0, s[4:5]
	s_mov_b32 m0, s64
	s_nop 0
	global_load_lds_dwordx4 v[216:217], off
	v_lshl_add_u64 v[216:217], s[38:39], 0, v[130:131]
	s_mov_b32 m0, s48
	v_lshl_add_u64 v[218:219], v[216:217], 0, s[0:1]
	global_load_lds_dwordx4 v[216:217], off
	s_mov_b32 m0, s49
	s_nop 0
	global_load_lds_dwordx4 v[218:219], off
	ds_read_b128 v[180:183], v142 offset:16384
	ds_read_b128 v[184:187], v142 offset:17408
	ds_read_b128 v[188:191], v142 offset:18432
	ds_read_b128 v[192:195], v142 offset:19456
	ds_read_b128 v[196:199], v142 offset:20480
	ds_read_b128 v[200:203], v142 offset:21504
	ds_read_b128 v[204:207], v142 offset:22528
	ds_read_b128 v[212:215], v142 offset:23552
	s_waitcnt vmcnt(8)
	s_waitcnt lgkmcnt(0)
	s_barrier
	s_waitcnt lgkmcnt(0)
	v_mfma_f32_16x16x32_bf16 v[60:63], v[144:147], v[180:183], v[60:63]
	v_mfma_f32_16x16x32_bf16 v[60:63], v[148:151], v[184:187], v[60:63]
	v_mfma_f32_16x16x32_bf16 v[48:51], v[152:155], v[180:183], v[48:51]
	v_mfma_f32_16x16x32_bf16 v[48:51], v[156:159], v[184:187], v[48:51]
	v_mfma_f32_16x16x32_bf16 v[56:59], v[160:163], v[180:183], v[56:59]
	v_mfma_f32_16x16x32_bf16 v[56:59], v[164:167], v[184:187], v[56:59]
	v_mfma_f32_16x16x32_bf16 v[52:55], v[172:175], v[180:183], v[52:55]
	v_mfma_f32_16x16x32_bf16 v[52:55], v[176:179], v[184:187], v[52:55]
	v_mfma_f32_16x16x32_bf16 v[36:39], v[172:175], v[188:191], v[36:39]
	v_mfma_f32_16x16x32_bf16 v[36:39], v[176:179], v[192:195], v[36:39]
	v_mfma_f32_16x16x32_bf16 v[40:43], v[160:163], v[188:191], v[40:43]
	v_mfma_f32_16x16x32_bf16 v[40:43], v[164:167], v[192:195], v[40:43]
	v_mfma_f32_16x16x32_bf16 v[32:35], v[152:155], v[188:191], v[32:35]
	v_mfma_f32_16x16x32_bf16 v[32:35], v[156:159], v[192:195], v[32:35]
	v_mfma_f32_16x16x32_bf16 v[44:47], v[144:147], v[188:191], v[44:47]
	v_mfma_f32_16x16x32_bf16 v[44:47], v[148:151], v[192:195], v[44:47]
	v_mfma_f32_16x16x32_bf16 v[28:31], v[144:147], v[196:199], v[28:31]
	v_mfma_f32_16x16x32_bf16 v[28:31], v[148:151], v[200:203], v[28:31]
	v_mfma_f32_16x16x32_bf16 v[16:19], v[152:155], v[196:199], v[16:19]
	v_mfma_f32_16x16x32_bf16 v[16:19], v[156:159], v[200:203], v[16:19]
	v_mfma_f32_16x16x32_bf16 v[24:27], v[160:163], v[196:199], v[24:27]
	v_mfma_f32_16x16x32_bf16 v[24:27], v[164:167], v[200:203], v[24:27]
	v_mfma_f32_16x16x32_bf16 v[20:23], v[172:175], v[196:199], v[20:23]
	v_mfma_f32_16x16x32_bf16 v[20:23], v[176:179], v[200:203], v[20:23]
	v_mfma_f32_16x16x32_bf16 v[4:7], v[172:175], v[204:207], v[4:7]
	v_mfma_f32_16x16x32_bf16 v[4:7], v[176:179], v[212:215], v[4:7]
	v_mfma_f32_16x16x32_bf16 v[8:11], v[160:163], v[204:207], v[8:11]
	v_mfma_f32_16x16x32_bf16 v[8:11], v[164:167], v[212:215], v[8:11]
	v_mfma_f32_16x16x32_bf16 v[0:3], v[152:155], v[204:207], v[0:3]
	v_mfma_f32_16x16x32_bf16 v[0:3], v[156:159], v[212:215], v[0:3]
	v_mfma_f32_16x16x32_bf16 v[12:15], v[144:147], v[204:207], v[12:15]
	v_mfma_f32_16x16x32_bf16 v[12:15], v[148:151], v[212:215], v[12:15]
	s_barrier
	s_mov_b32 m0, s50
	v_lshl_add_u64 v[218:219], v[216:217], 0, s[2:3]
	global_load_lds_dwordx4 v[218:219], off
	v_lshl_add_u64 v[218:219], v[216:217], 0, s[4:5]
	s_mov_b32 m0, s51
	s_nop 0
	global_load_lds_dwordx4 v[218:219], off
	ds_read_b128 v[144:147], v143
	ds_read_b128 v[148:151], v143 offset:1024
	ds_read_b128 v[152:155], v143 offset:2048
	ds_read_b128 v[156:159], v143 offset:3072
	ds_read_b128 v[160:163], v136
	ds_read_b128 v[164:167], v136 offset:1024
	ds_read_b128 v[172:175], v136 offset:2048
	ds_read_b128 v[176:179], v136 offset:3072
	ds_read_b128 v[180:183], v142 offset:32768
	ds_read_b128 v[184:187], v142 offset:33792
	ds_read_b128 v[188:191], v142 offset:34816
	ds_read_b128 v[192:195], v142 offset:35840
	ds_read_b128 v[196:199], v142 offset:36864
	ds_read_b128 v[200:203], v142 offset:37888
	ds_read_b128 v[204:207], v142 offset:38912
	ds_read_b128 v[212:215], v142 offset:39936
	s_waitcnt vmcnt(8)
	s_waitcnt lgkmcnt(0)
	s_barrier
	s_waitcnt lgkmcnt(0)
	v_mfma_f32_16x16x32_bf16 v[124:127], v[144:147], v[180:183], v[124:127]
	v_mfma_f32_16x16x32_bf16 v[124:127], v[148:151], v[184:187], v[124:127]
	v_mfma_f32_16x16x32_bf16 v[112:115], v[152:155], v[180:183], v[112:115]
	v_mfma_f32_16x16x32_bf16 v[112:115], v[156:159], v[184:187], v[112:115]
	v_mfma_f32_16x16x32_bf16 v[120:123], v[160:163], v[180:183], v[120:123]
	v_mfma_f32_16x16x32_bf16 v[120:123], v[164:167], v[184:187], v[120:123]
	v_mfma_f32_16x16x32_bf16 v[116:119], v[172:175], v[180:183], v[116:119]
	v_mfma_f32_16x16x32_bf16 v[116:119], v[176:179], v[184:187], v[116:119]
	v_mfma_f32_16x16x32_bf16 v[100:103], v[172:175], v[188:191], v[100:103]
	v_mfma_f32_16x16x32_bf16 v[100:103], v[176:179], v[192:195], v[100:103]
	v_mfma_f32_16x16x32_bf16 v[104:107], v[160:163], v[188:191], v[104:107]
	v_mfma_f32_16x16x32_bf16 v[104:107], v[164:167], v[192:195], v[104:107]
	v_mfma_f32_16x16x32_bf16 v[96:99], v[152:155], v[188:191], v[96:99]
	v_mfma_f32_16x16x32_bf16 v[96:99], v[156:159], v[192:195], v[96:99]
	v_mfma_f32_16x16x32_bf16 v[108:111], v[144:147], v[188:191], v[108:111]
	v_mfma_f32_16x16x32_bf16 v[108:111], v[148:151], v[192:195], v[108:111]
	v_mfma_f32_16x16x32_bf16 v[92:95], v[144:147], v[196:199], v[92:95]
	v_mfma_f32_16x16x32_bf16 v[92:95], v[148:151], v[200:203], v[92:95]
	v_mfma_f32_16x16x32_bf16 v[80:83], v[152:155], v[196:199], v[80:83]
	v_mfma_f32_16x16x32_bf16 v[80:83], v[156:159], v[200:203], v[80:83]
	v_mfma_f32_16x16x32_bf16 v[88:91], v[160:163], v[196:199], v[88:91]
	v_mfma_f32_16x16x32_bf16 v[88:91], v[164:167], v[200:203], v[88:91]
	v_mfma_f32_16x16x32_bf16 v[84:87], v[172:175], v[196:199], v[84:87]
	v_mfma_f32_16x16x32_bf16 v[84:87], v[176:179], v[200:203], v[84:87]
	v_mfma_f32_16x16x32_bf16 v[68:71], v[172:175], v[204:207], v[68:71]
	v_mfma_f32_16x16x32_bf16 v[68:71], v[176:179], v[212:215], v[68:71]
	v_mfma_f32_16x16x32_bf16 v[72:75], v[160:163], v[204:207], v[72:75]
	v_mfma_f32_16x16x32_bf16 v[72:75], v[164:167], v[212:215], v[72:75]
	v_mfma_f32_16x16x32_bf16 v[64:67], v[152:155], v[204:207], v[64:67]
	v_mfma_f32_16x16x32_bf16 v[64:67], v[156:159], v[212:215], v[64:67]
	v_mfma_f32_16x16x32_bf16 v[76:79], v[144:147], v[204:207], v[76:79]
	v_mfma_f32_16x16x32_bf16 v[76:79], v[148:151], v[212:215], v[76:79]
	s_barrier
	s_mov_b32 m0, s69
	v_lshl_add_u64 v[218:219], v[208:209], 0, s[10:11]
	global_load_lds_dwordx4 v[218:219], off
	v_lshl_add_u64 v[218:219], v[208:209], 0, s[12:13]
	s_mov_b32 m0, s70
	s_nop 0
	global_load_lds_dwordx4 v[218:219], off
	v_lshl_add_u64 v[218:219], v[208:209], 0, s[14:15]
	s_mov_b32 m0, s71
	v_lshl_add_u64 v[208:209], v[208:209], 0, s[16:17]
	global_load_lds_dwordx4 v[218:219], off
	s_mov_b32 m0, s72
	s_nop 0
	global_load_lds_dwordx4 v[208:209], off
	v_lshl_add_u64 v[208:209], v[216:217], 0, s[10:11]
	s_mov_b32 m0, s53
	s_nop 0
	global_load_lds_dwordx4 v[208:209], off
	v_lshl_add_u64 v[208:209], v[216:217], 0, s[12:13]
	s_mov_b32 m0, s54
	s_nop 0
	global_load_lds_dwordx4 v[208:209], off
	ds_read_b128 v[180:183], v142 offset:49152
	ds_read_b128 v[184:187], v142 offset:50176
	ds_read_b128 v[188:191], v142 offset:51200
	ds_read_b128 v[192:195], v142 offset:52224
	ds_read_b128 v[196:199], v142 offset:53248
	ds_read_b128 v[200:203], v142 offset:54272
	ds_read_b128 v[204:207], v142 offset:55296
	ds_read_b128 v[212:215], v142 offset:56320
	s_waitcnt vmcnt(8)
	s_waitcnt lgkmcnt(0)
	s_barrier
	s_waitcnt lgkmcnt(0)
	v_mfma_f32_16x16x32_bf16 v[60:63], v[144:147], v[180:183], v[60:63]
	v_mfma_f32_16x16x32_bf16 v[60:63], v[148:151], v[184:187], v[60:63]
	v_mfma_f32_16x16x32_bf16 v[48:51], v[152:155], v[180:183], v[48:51]
	v_mfma_f32_16x16x32_bf16 v[48:51], v[156:159], v[184:187], v[48:51]
	v_mfma_f32_16x16x32_bf16 v[56:59], v[160:163], v[180:183], v[56:59]
	v_mfma_f32_16x16x32_bf16 v[56:59], v[164:167], v[184:187], v[56:59]
	v_mfma_f32_16x16x32_bf16 v[52:55], v[172:175], v[180:183], v[52:55]
	v_mfma_f32_16x16x32_bf16 v[52:55], v[176:179], v[184:187], v[52:55]
	v_mfma_f32_16x16x32_bf16 v[36:39], v[172:175], v[188:191], v[36:39]
	v_mfma_f32_16x16x32_bf16 v[36:39], v[176:179], v[192:195], v[36:39]
	v_mfma_f32_16x16x32_bf16 v[40:43], v[160:163], v[188:191], v[40:43]
	v_mfma_f32_16x16x32_bf16 v[40:43], v[164:167], v[192:195], v[40:43]
	v_mfma_f32_16x16x32_bf16 v[32:35], v[152:155], v[188:191], v[32:35]
	v_mfma_f32_16x16x32_bf16 v[32:35], v[156:159], v[192:195], v[32:35]
	v_mfma_f32_16x16x32_bf16 v[44:47], v[144:147], v[188:191], v[44:47]
	v_mfma_f32_16x16x32_bf16 v[44:47], v[148:151], v[192:195], v[44:47]
	v_mfma_f32_16x16x32_bf16 v[28:31], v[144:147], v[196:199], v[28:31]
	v_mfma_f32_16x16x32_bf16 v[28:31], v[148:151], v[200:203], v[28:31]
	v_mfma_f32_16x16x32_bf16 v[16:19], v[152:155], v[196:199], v[16:19]
	v_mfma_f32_16x16x32_bf16 v[16:19], v[156:159], v[200:203], v[16:19]
	v_mfma_f32_16x16x32_bf16 v[24:27], v[160:163], v[196:199], v[24:27]
	v_mfma_f32_16x16x32_bf16 v[24:27], v[164:167], v[200:203], v[24:27]
	v_mfma_f32_16x16x32_bf16 v[20:23], v[172:175], v[196:199], v[20:23]
	v_mfma_f32_16x16x32_bf16 v[20:23], v[176:179], v[200:203], v[20:23]
	v_mfma_f32_16x16x32_bf16 v[4:7], v[172:175], v[204:207], v[4:7]
	v_mfma_f32_16x16x32_bf16 v[4:7], v[176:179], v[212:215], v[4:7]
	v_mfma_f32_16x16x32_bf16 v[8:11], v[160:163], v[204:207], v[8:11]
	v_mfma_f32_16x16x32_bf16 v[8:11], v[164:167], v[212:215], v[8:11]
	v_mfma_f32_16x16x32_bf16 v[0:3], v[152:155], v[204:207], v[0:3]
	v_mfma_f32_16x16x32_bf16 v[0:3], v[156:159], v[212:215], v[0:3]
	v_mfma_f32_16x16x32_bf16 v[12:15], v[144:147], v[204:207], v[12:15]
	v_mfma_f32_16x16x32_bf16 v[12:15], v[148:151], v[212:215], v[12:15]
	s_barrier
	s_cmp_gt_u32 s21, 13
	s_cbranch_scc0 .LBB0_970
	s_and_b64 vcc, exec, s[18:19]
	s_cbranch_vccz .LBB0_973
	s_barrier

.LBB0_1046:
	s_add_i32 s55, s55, 2
	s_mov_b32 s56, s55
	s_ashr_i32 s57, s56, 31
	s_lshl_b64 s[58:59], s[56:57], 7
	s_add_u32 s57, s58, 0x100
	s_addc_u32 s60, s59, 0
	s_add_u32 s61, s24, s57
	s_addc_u32 s62, s25, s60
	s_add_u32 s63, s22, s57
	s_addc_u32 s60, s23, s60
	s_cmp_eq_u32 s56, 42
	s_cselect_b32 s57, s1, s62
	s_cselect_b32 s56, s0, s61
	s_cselect_b32 s61, s27, s60
	s_cselect_b32 s60, s26, s63
	v_lshl_add_u64 v[208:209], v[136:137], 0, s[58:59]
	v_lshl_add_u64 v[216:217], v[208:209], 0, s[12:13]
	s_add_i32 m0, s39, 0xc000
	s_nop 0
	global_load_lds_dwordx4 v[216:217], off
	v_lshl_add_u64 v[208:209], v[208:209], 0, s[14:15]
	s_add_i32 m0, s39, 0xe000
	s_nop 0
	global_load_lds_dwordx4 v[208:209], off
	ds_read_b128 v[144:147], v140
	ds_read_b128 v[148:151], v140 offset:1024
	ds_read_b128 v[152:155], v140 offset:2048
	ds_read_b128 v[156:159], v140 offset:3072
	ds_read_b128 v[160:163], v141
	ds_read_b128 v[164:167], v141 offset:1024
	ds_read_b128 v[172:175], v141 offset:2048
	ds_read_b128 v[176:179], v141 offset:3072
	ds_read_b128 v[180:183], v142
	ds_read_b128 v[184:187], v142 offset:1024
	ds_read_b128 v[188:191], v142 offset:2048
	ds_read_b128 v[192:195], v142 offset:3072
	ds_read_b128 v[196:199], v142 offset:4096
	ds_read_b128 v[200:203], v142 offset:5120
	ds_read_b128 v[204:207], v142 offset:6144
	ds_read_b128 v[212:215], v142 offset:7168
	s_waitcnt vmcnt(8)
	s_waitcnt lgkmcnt(0)
	s_barrier
	s_waitcnt lgkmcnt(0)
	v_mfma_f32_16x16x32_bf16 v[124:127], v[144:147], v[180:183], v[124:127]
	v_mfma_f32_16x16x32_bf16 v[124:127], v[148:151], v[184:187], v[124:127]
	v_mfma_f32_16x16x32_bf16 v[120:123], v[152:155], v[180:183], v[120:123]
	v_mfma_f32_16x16x32_bf16 v[120:123], v[156:159], v[184:187], v[120:123]
	v_mfma_f32_16x16x32_bf16 v[108:111], v[160:163], v[180:183], v[108:111]
	v_mfma_f32_16x16x32_bf16 v[108:111], v[164:167], v[184:187], v[108:111]
	v_mfma_f32_16x16x32_bf16 v[104:107], v[172:175], v[180:183], v[104:107]
	v_mfma_f32_16x16x32_bf16 v[104:107], v[176:179], v[184:187], v[104:107]
	v_mfma_f32_16x16x32_bf16 v[88:91], v[172:175], v[188:191], v[88:91]
	v_mfma_f32_16x16x32_bf16 v[88:91], v[176:179], v[192:195], v[88:91]
	v_mfma_f32_16x16x32_bf16 v[92:95], v[160:163], v[188:191], v[92:95]
	v_mfma_f32_16x16x32_bf16 v[92:95], v[164:167], v[192:195], v[92:95]
	v_mfma_f32_16x16x32_bf16 v[112:115], v[152:155], v[188:191], v[112:115]
	v_mfma_f32_16x16x32_bf16 v[112:115], v[156:159], v[192:195], v[112:115]
	v_mfma_f32_16x16x32_bf16 v[116:119], v[144:147], v[188:191], v[116:119]
	v_mfma_f32_16x16x32_bf16 v[116:119], v[148:151], v[192:195], v[116:119]
	v_mfma_f32_16x16x32_bf16 v[100:103], v[144:147], v[196:199], v[100:103]
	v_mfma_f32_16x16x32_bf16 v[100:103], v[148:151], v[200:203], v[100:103]
	v_mfma_f32_16x16x32_bf16 v[96:99], v[152:155], v[196:199], v[96:99]
	v_mfma_f32_16x16x32_bf16 v[96:99], v[156:159], v[200:203], v[96:99]
	v_mfma_f32_16x16x32_bf16 v[76:79], v[160:163], v[196:199], v[76:79]
	v_mfma_f32_16x16x32_bf16 v[76:79], v[164:167], v[200:203], v[76:79]
	v_mfma_f32_16x16x32_bf16 v[72:75], v[172:175], v[196:199], v[72:75]
	v_mfma_f32_16x16x32_bf16 v[72:75], v[176:179], v[200:203], v[72:75]
	v_mfma_f32_16x16x32_bf16 v[64:67], v[172:175], v[204:207], v[64:67]
	v_mfma_f32_16x16x32_bf16 v[64:67], v[176:179], v[212:215], v[64:67]
	v_mfma_f32_16x16x32_bf16 v[68:71], v[160:163], v[204:207], v[68:71]
	v_mfma_f32_16x16x32_bf16 v[68:71], v[164:167], v[212:215], v[68:71]
	v_mfma_f32_16x16x32_bf16 v[80:83], v[152:155], v[204:207], v[80:83]
	v_mfma_f32_16x16x32_bf16 v[80:83], v[156:159], v[212:215], v[80:83]
	v_mfma_f32_16x16x32_bf16 v[84:87], v[144:147], v[204:207], v[84:87]
	v_mfma_f32_16x16x32_bf16 v[84:87], v[148:151], v[212:215], v[84:87]
	s_barrier
	s_add_i32 s58, s49, s38
	v_lshl_add_u64 v[208:209], s[60:61], 0, v[130:131]
	s_mov_b32 m0, s58
	s_nop 0
	global_load_lds_dwordx4 v[208:209], off
	v_lshl_add_u64 v[216:217], v[208:209], 0, s[2:3]
	s_add_i32 m0, s58, 0x2000
	s_add_i32 s58, s50, s38
	global_load_lds_dwordx4 v[216:217], off
	v_lshl_add_u64 v[216:217], v[208:209], 0, s[4:5]
	s_mov_b32 m0, s58
	s_nop 0
	global_load_lds_dwordx4 v[216:217], off
	v_lshl_add_u64 v[216:217], v[208:209], 0, s[6:7]
	s_add_i32 m0, s58, 0x2000
	s_nop 0
	global_load_lds_dwordx4 v[216:217], off
	v_lshl_add_u64 v[216:217], s[56:57], 0, v[128:129]
	s_mov_b32 m0, s39
	v_lshl_add_u64 v[218:219], v[216:217], 0, s[2:3]
	global_load_lds_dwordx4 v[216:217], off
	s_mov_b32 m0, s40
	s_nop 0
	global_load_lds_dwordx4 v[218:219], off
	ds_read_b128 v[180:183], v142 offset:16384
	ds_read_b128 v[184:187], v142 offset:17408
	ds_read_b128 v[188:191], v142 offset:18432
	ds_read_b128 v[192:195], v142 offset:19456
	ds_read_b128 v[196:199], v142 offset:20480
	ds_read_b128 v[200:203], v142 offset:21504
	ds_read_b128 v[204:207], v142 offset:22528
	ds_read_b128 v[212:215], v142 offset:23552
	s_waitcnt vmcnt(8)
	s_waitcnt lgkmcnt(0)
	s_barrier
	s_waitcnt lgkmcnt(0)
	v_mfma_f32_16x16x32_bf16 v[60:63], v[144:147], v[180:183], v[60:63]
	v_mfma_f32_16x16x32_bf16 v[60:63], v[148:151], v[184:187], v[60:63]
	v_mfma_f32_16x16x32_bf16 v[56:59], v[152:155], v[180:183], v[56:59]
	v_mfma_f32_16x16x32_bf16 v[56:59], v[156:159], v[184:187], v[56:59]
	v_mfma_f32_16x16x32_bf16 v[44:47], v[160:163], v[180:183], v[44:47]
	v_mfma_f32_16x16x32_bf16 v[44:47], v[164:167], v[184:187], v[44:47]
	v_mfma_f32_16x16x32_bf16 v[40:43], v[172:175], v[180:183], v[40:43]
	v_mfma_f32_16x16x32_bf16 v[40:43], v[176:179], v[184:187], v[40:43]
	v_mfma_f32_16x16x32_bf16 v[24:27], v[172:175], v[188:191], v[24:27]
	v_mfma_f32_16x16x32_bf16 v[24:27], v[176:179], v[192:195], v[24:27]
	v_mfma_f32_16x16x32_bf16 v[28:31], v[160:163], v[188:191], v[28:31]
	v_mfma_f32_16x16x32_bf16 v[28:31], v[164:167], v[192:195], v[28:31]
	v_mfma_f32_16x16x32_bf16 v[48:51], v[152:155], v[188:191], v[48:51]
	v_mfma_f32_16x16x32_bf16 v[48:51], v[156:159], v[192:195], v[48:51]
	v_mfma_f32_16x16x32_bf16 v[52:55], v[144:147], v[188:191], v[52:55]
	v_mfma_f32_16x16x32_bf16 v[52:55], v[148:151], v[192:195], v[52:55]
	v_mfma_f32_16x16x32_bf16 v[36:39], v[144:147], v[196:199], v[36:39]
	v_mfma_f32_16x16x32_bf16 v[36:39], v[148:151], v[200:203], v[36:39]
	v_mfma_f32_16x16x32_bf16 v[32:35], v[152:155], v[196:199], v[32:35]
	v_mfma_f32_16x16x32_bf16 v[32:35], v[156:159], v[200:203], v[32:35]
	v_mfma_f32_16x16x32_bf16 v[12:15], v[160:163], v[196:199], v[12:15]
	v_mfma_f32_16x16x32_bf16 v[12:15], v[164:167], v[200:203], v[12:15]
	v_mfma_f32_16x16x32_bf16 v[8:11], v[172:175], v[196:199], v[8:11]
	v_mfma_f32_16x16x32_bf16 v[8:11], v[176:179], v[200:203], v[8:11]
	v_mfma_f32_16x16x32_bf16 v[0:3], v[172:175], v[204:207], v[0:3]
	v_mfma_f32_16x16x32_bf16 v[0:3], v[176:179], v[212:215], v[0:3]
	v_mfma_f32_16x16x32_bf16 v[4:7], v[160:163], v[204:207], v[4:7]
	v_mfma_f32_16x16x32_bf16 v[4:7], v[164:167], v[212:215], v[4:7]
	v_mfma_f32_16x16x32_bf16 v[16:19], v[152:155], v[204:207], v[16:19]
	v_mfma_f32_16x16x32_bf16 v[16:19], v[156:159], v[212:215], v[16:19]
	v_mfma_f32_16x16x32_bf16 v[20:23], v[144:147], v[204:207], v[20:23]
	v_mfma_f32_16x16x32_bf16 v[20:23], v[148:151], v[212:215], v[20:23]
	s_barrier
	s_mov_b32 m0, s41
	v_lshl_add_u64 v[218:219], v[216:217], 0, s[4:5]
	global_load_lds_dwordx4 v[218:219], off
	v_lshl_add_u64 v[218:219], v[216:217], 0, s[6:7]
	s_mov_b32 m0, s42
	s_nop 0
	global_load_lds_dwordx4 v[218:219], off
	s_add_i32 s56, 0, 0x18000
	v_add_u32_e32 v143, s56, v139
	s_add_i32 s57, 0, 0x1c000
	ds_read_b128 v[144:147], v143
	ds_read_b128 v[148:151], v143 offset:1024
	ds_read_b128 v[152:155], v143 offset:2048
	ds_read_b128 v[156:159], v143 offset:3072
	v_add_u32_e32 v143, s57, v139
	ds_read_b128 v[160:163], v143
	ds_read_b128 v[164:167], v143 offset:1024
	ds_read_b128 v[172:175], v143 offset:2048
	ds_read_b128 v[176:179], v143 offset:3072
	ds_read_b128 v[180:183], v142 offset:32768
	ds_read_b128 v[184:187], v142 offset:33792
	ds_read_b128 v[188:191], v142 offset:34816
	ds_read_b128 v[192:195], v142 offset:35840
	ds_read_b128 v[196:199], v142 offset:36864
	ds_read_b128 v[200:203], v142 offset:37888
	ds_read_b128 v[204:207], v142 offset:38912
	ds_read_b128 v[212:215], v142 offset:39936
	s_nop 0
	s_waitcnt vmcnt(8)
	s_waitcnt lgkmcnt(0)
	s_barrier
	s_waitcnt lgkmcnt(0)
	v_mfma_f32_16x16x32_bf16 v[124:127], v[144:147], v[180:183], v[124:127]
	v_mfma_f32_16x16x32_bf16 v[124:127], v[148:151], v[184:187], v[124:127]
	v_mfma_f32_16x16x32_bf16 v[120:123], v[152:155], v[180:183], v[120:123]
	v_mfma_f32_16x16x32_bf16 v[120:123], v[156:159], v[184:187], v[120:123]
	v_mfma_f32_16x16x32_bf16 v[108:111], v[160:163], v[180:183], v[108:111]
	v_mfma_f32_16x16x32_bf16 v[108:111], v[164:167], v[184:187], v[108:111]
	v_mfma_f32_16x16x32_bf16 v[104:107], v[172:175], v[180:183], v[104:107]
	v_mfma_f32_16x16x32_bf16 v[104:107], v[176:179], v[184:187], v[104:107]
	v_mfma_f32_16x16x32_bf16 v[88:91], v[172:175], v[188:191], v[88:91]
	v_mfma_f32_16x16x32_bf16 v[88:91], v[176:179], v[192:195], v[88:91]
	v_mfma_f32_16x16x32_bf16 v[92:95], v[160:163], v[188:191], v[92:95]
	v_mfma_f32_16x16x32_bf16 v[92:95], v[164:167], v[192:195], v[92:95]
	v_mfma_f32_16x16x32_bf16 v[112:115], v[152:155], v[188:191], v[112:115]
	v_mfma_f32_16x16x32_bf16 v[112:115], v[156:159], v[192:195], v[112:115]
	v_mfma_f32_16x16x32_bf16 v[116:119], v[144:147], v[188:191], v[116:119]
	v_mfma_f32_16x16x32_bf16 v[116:119], v[148:151], v[192:195], v[116:119]
	v_mfma_f32_16x16x32_bf16 v[100:103], v[144:147], v[196:199], v[100:103]
	v_mfma_f32_16x16x32_bf16 v[100:103], v[148:151], v[200:203], v[100:103]
	v_mfma_f32_16x16x32_bf16 v[96:99], v[152:155], v[196:199], v[96:99]
	v_mfma_f32_16x16x32_bf16 v[96:99], v[156:159], v[200:203], v[96:99]
	v_mfma_f32_16x16x32_bf16 v[76:79], v[160:163], v[196:199], v[76:79]
	v_mfma_f32_16x16x32_bf16 v[76:79], v[164:167], v[200:203], v[76:79]
	v_mfma_f32_16x16x32_bf16 v[72:75], v[172:175], v[196:199], v[72:75]
	v_mfma_f32_16x16x32_bf16 v[72:75], v[176:179], v[200:203], v[72:75]
	v_mfma_f32_16x16x32_bf16 v[64:67], v[172:175], v[204:207], v[64:67]
	v_mfma_f32_16x16x32_bf16 v[64:67], v[176:179], v[212:215], v[64:67]
	v_mfma_f32_16x16x32_bf16 v[68:71], v[160:163], v[204:207], v[68:71]
	v_mfma_f32_16x16x32_bf16 v[68:71], v[164:167], v[212:215], v[68:71]
	v_mfma_f32_16x16x32_bf16 v[80:83], v[152:155], v[204:207], v[80:83]
	v_mfma_f32_16x16x32_bf16 v[80:83], v[156:159], v[212:215], v[80:83]
	v_mfma_f32_16x16x32_bf16 v[84:87], v[144:147], v[204:207], v[84:87]
	v_mfma_f32_16x16x32_bf16 v[84:87], v[148:151], v[212:215], v[84:87]
	s_barrier
	s_add_i32 s56, s56, s38
	v_lshl_add_u64 v[218:219], v[208:209], 0, s[12:13]
	s_mov_b32 m0, s56
	s_nop 0
	global_load_lds_dwordx4 v[218:219], off
	v_lshl_add_u64 v[218:219], v[208:209], 0, s[14:15]
	s_add_i32 m0, s56, 0x2000
	s_add_i32 s56, s57, s38
	global_load_lds_dwordx4 v[218:219], off
	v_lshl_add_u64 v[218:219], v[208:209], 0, s[16:17]
	s_mov_b32 m0, s56
	v_lshl_add_u64 v[208:209], v[208:209], 0, s[18:19]
	global_load_lds_dwordx4 v[218:219], off
	s_add_i32 m0, s56, 0x2000
	s_nop 0
	global_load_lds_dwordx4 v[208:209], off
	v_lshl_add_u64 v[208:209], v[216:217], 0, s[12:13]
	s_mov_b32 m0, s44
	s_nop 0
	global_load_lds_dwordx4 v[208:209], off
	v_lshl_add_u64 v[208:209], v[216:217], 0, s[14:15]
	s_mov_b32 m0, s45
	s_nop 0
	global_load_lds_dwordx4 v[208:209], off
	ds_read_b128 v[180:183], v142 offset:49152
	ds_read_b128 v[184:187], v142 offset:50176
	ds_read_b128 v[188:191], v142 offset:51200
	ds_read_b128 v[192:195], v142 offset:52224
	ds_read_b128 v[196:199], v142 offset:53248
	ds_read_b128 v[200:203], v142 offset:54272
	ds_read_b128 v[204:207], v142 offset:55296
	ds_read_b128 v[212:215], v142 offset:56320
	s_waitcnt vmcnt(8)
	s_waitcnt lgkmcnt(0)
	s_barrier
	s_waitcnt lgkmcnt(0)
	v_mfma_f32_16x16x32_bf16 v[60:63], v[144:147], v[180:183], v[60:63]
	v_mfma_f32_16x16x32_bf16 v[60:63], v[148:151], v[184:187], v[60:63]
	v_mfma_f32_16x16x32_bf16 v[56:59], v[152:155], v[180:183], v[56:59]
	v_mfma_f32_16x16x32_bf16 v[56:59], v[156:159], v[184:187], v[56:59]
	v_mfma_f32_16x16x32_bf16 v[44:47], v[160:163], v[180:183], v[44:47]
	v_mfma_f32_16x16x32_bf16 v[44:47], v[164:167], v[184:187], v[44:47]
	v_mfma_f32_16x16x32_bf16 v[40:43], v[172:175], v[180:183], v[40:43]
	v_mfma_f32_16x16x32_bf16 v[40:43], v[176:179], v[184:187], v[40:43]
	v_mfma_f32_16x16x32_bf16 v[24:27], v[172:175], v[188:191], v[24:27]
	v_mfma_f32_16x16x32_bf16 v[24:27], v[176:179], v[192:195], v[24:27]
	v_mfma_f32_16x16x32_bf16 v[28:31], v[160:163], v[188:191], v[28:31]
	v_mfma_f32_16x16x32_bf16 v[28:31], v[164:167], v[192:195], v[28:31]
	v_mfma_f32_16x16x32_bf16 v[48:51], v[152:155], v[188:191], v[48:51]
	v_mfma_f32_16x16x32_bf16 v[48:51], v[156:159], v[192:195], v[48:51]
	v_mfma_f32_16x16x32_bf16 v[52:55], v[144:147], v[188:191], v[52:55]
	v_mfma_f32_16x16x32_bf16 v[52:55], v[148:151], v[192:195], v[52:55]
	v_mfma_f32_16x16x32_bf16 v[36:39], v[144:147], v[196:199], v[36:39]
	v_mfma_f32_16x16x32_bf16 v[36:39], v[148:151], v[200:203], v[36:39]
	v_mfma_f32_16x16x32_bf16 v[32:35], v[152:155], v[196:199], v[32:35]
	v_mfma_f32_16x16x32_bf16 v[32:35], v[156:159], v[200:203], v[32:35]
	v_mfma_f32_16x16x32_bf16 v[12:15], v[160:163], v[196:199], v[12:15]
	v_mfma_f32_16x16x32_bf16 v[12:15], v[164:167], v[200:203], v[12:15]
	v_mfma_f32_16x16x32_bf16 v[8:11], v[172:175], v[196:199], v[8:11]
	v_mfma_f32_16x16x32_bf16 v[8:11], v[176:179], v[200:203], v[8:11]
	v_mfma_f32_16x16x32_bf16 v[0:3], v[172:175], v[204:207], v[0:3]
	v_mfma_f32_16x16x32_bf16 v[0:3], v[176:179], v[212:215], v[0:3]
	v_mfma_f32_16x16x32_bf16 v[4:7], v[160:163], v[204:207], v[4:7]
	v_mfma_f32_16x16x32_bf16 v[4:7], v[164:167], v[212:215], v[4:7]
	v_mfma_f32_16x16x32_bf16 v[16:19], v[152:155], v[204:207], v[16:19]
	v_mfma_f32_16x16x32_bf16 v[16:19], v[156:159], v[212:215], v[16:19]
	v_mfma_f32_16x16x32_bf16 v[20:23], v[144:147], v[204:207], v[20:23]
	v_mfma_f32_16x16x32_bf16 v[20:23], v[148:151], v[212:215], v[20:23]
	s_barrier
	s_cmp_gt_u32 s55, 41
	s_cbranch_scc0 .LBB0_1046
	s_and_b64 vcc, exec, s[20:21]
	s_cbranch_vccz .LBB0_1049
	s_barrier
